# v8 + B-operand-only responsibility-split L2 prefetch: one 8-lane dword LDS-DMA touch per wave per iteration, each CU touches its 1/8 (32 rows) of the weight-tile lines of K-tiles t+3,t+4
# speedup vs baseline: 1.0161x; 1.0161x over previous
.LBB0_340:
	s_and_b32 s98, s55, 3
	s_and_b32 s99, s54, 7
	s_lshl_b32 s98, s98, 6
	s_lshl_b32 s99, s99, 5
	v_and_b32_e32 v244, 63, v0
	v_and_b32_e32 v244, 7, v244
	v_lshrrev_b32_e32 v245, 6, v0
	v_lshl_add_u32 v244, v245, 3, v244
	v_add_u32_e32 v244, 0x80, v244
	v_cmp_gt_u32_e32 vcc, 0x80, v244
	v_and_b32_e32 v245, 63, v244
	v_add_u32_e32 v245, s98, v245
	v_lshrrev_b32_e32 v246, 6, v244
	v_subrev_u32_e32 v247, 0x80, v244
	v_and_b32_e32 v248, 31, v247
	v_add_u32_e32 v248, s99, v248
	v_lshrrev_b32_e32 v247, 5, v247
	v_cndmask_b32_e32 v245, v248, v245, vcc
	v_cndmask_b32_e32 v246, v247, v246, vcc
	v_lshlrev_b32_e32 v245, 13, v245
	v_lshl_add_u32 v245, v246, 7, v245
	v_add_u32_e32 v244, 0x80, v245
	v_mov_b32_e32 v245, 0
	v_mov_b32_e32 v246, s12
	v_mov_b32_e32 v247, s13
	v_mov_b32_e32 v248, s14
	v_mov_b32_e32 v249, s15
	v_cndmask_b32_e32 v246, v248, v246, vcc
	v_cndmask_b32_e32 v247, v249, v247, vcc
	v_lshl_add_u64 v[242:243], v[246:247], 0, v[244:245]
	v_add_u32_e32 v252, 0x10000, v159
	s_add_u32 s12, s12, 0x100080
	s_addc_u32 s13, s13, 0
	s_add_u32 s0, s14, 0x100
	v_mov_b32_e32 v2, 0
	s_addc_u32 s1, s15, 0
	s_mov_b32 s39, -2
	v_mov_b32_e32 v3, v2
	v_mov_b32_e32 v4, v2
	v_mov_b32_e32 v5, v2
	v_mov_b32_e32 v6, v2
	v_mov_b32_e32 v7, v2
	v_mov_b32_e32 v8, v2
	v_mov_b32_e32 v9, v2
	v_mov_b32_e32 v18, v2
	v_mov_b32_e32 v19, v2
	v_mov_b32_e32 v20, v2
	v_mov_b32_e32 v21, v2
	v_mov_b32_e32 v22, v2
	v_mov_b32_e32 v23, v2
	v_mov_b32_e32 v24, v2
	v_mov_b32_e32 v25, v2
	v_mov_b32_e32 v34, v2
	v_mov_b32_e32 v35, v2
	v_mov_b32_e32 v36, v2
	v_mov_b32_e32 v37, v2
	v_mov_b32_e32 v38, v2
	v_mov_b32_e32 v39, v2
	v_mov_b32_e32 v40, v2
	v_mov_b32_e32 v41, v2
	v_mov_b32_e32 v50, v2
	v_mov_b32_e32 v51, v2
	v_mov_b32_e32 v52, v2
	v_mov_b32_e32 v53, v2
	v_mov_b32_e32 v54, v2
	v_mov_b32_e32 v55, v2
	v_mov_b32_e32 v56, v2
	v_mov_b32_e32 v57, v2
	v_mov_b32_e32 v10, v2
	v_mov_b32_e32 v11, v2
	v_mov_b32_e32 v12, v2
	v_mov_b32_e32 v13, v2
	v_mov_b32_e32 v14, v2
	v_mov_b32_e32 v15, v2
	v_mov_b32_e32 v16, v2
	v_mov_b32_e32 v17, v2
	v_mov_b32_e32 v26, v2
	v_mov_b32_e32 v27, v2
	v_mov_b32_e32 v28, v2
	v_mov_b32_e32 v29, v2
	v_mov_b32_e32 v30, v2
	v_mov_b32_e32 v31, v2
	v_mov_b32_e32 v32, v2
	v_mov_b32_e32 v33, v2
	v_mov_b32_e32 v42, v2
	v_mov_b32_e32 v43, v2
	v_mov_b32_e32 v44, v2
	v_mov_b32_e32 v45, v2
	v_mov_b32_e32 v46, v2
	v_mov_b32_e32 v47, v2
	v_mov_b32_e32 v48, v2
	v_mov_b32_e32 v49, v2
	v_mov_b32_e32 v58, v2
	v_mov_b32_e32 v59, v2
	v_mov_b32_e32 v60, v2
	v_mov_b32_e32 v61, v2
	v_mov_b32_e32 v62, v2
	v_mov_b32_e32 v63, v2
	v_mov_b32_e32 v64, v2
	v_mov_b32_e32 v65, v2
	v_mov_b32_e32 v66, v2
	v_mov_b32_e32 v67, v2
	v_mov_b32_e32 v68, v2
	v_mov_b32_e32 v69, v2
	v_mov_b32_e32 v70, v2
	v_mov_b32_e32 v71, v2
	v_mov_b32_e32 v72, v2
	v_mov_b32_e32 v73, v2
	v_mov_b32_e32 v82, v2
	v_mov_b32_e32 v83, v2
	v_mov_b32_e32 v84, v2
	v_mov_b32_e32 v85, v2
	v_mov_b32_e32 v86, v2
	v_mov_b32_e32 v87, v2
	v_mov_b32_e32 v88, v2
	v_mov_b32_e32 v89, v2
	v_mov_b32_e32 v98, v2
	v_mov_b32_e32 v99, v2
	v_mov_b32_e32 v100, v2
	v_mov_b32_e32 v101, v2
	v_mov_b32_e32 v102, v2
	v_mov_b32_e32 v103, v2
	v_mov_b32_e32 v104, v2
	v_mov_b32_e32 v105, v2
	v_mov_b32_e32 v114, v2
	v_mov_b32_e32 v115, v2
	v_mov_b32_e32 v116, v2
	v_mov_b32_e32 v117, v2
	v_mov_b32_e32 v118, v2
	v_mov_b32_e32 v119, v2
	v_mov_b32_e32 v120, v2
	v_mov_b32_e32 v121, v2
	v_mov_b32_e32 v74, v2
	v_mov_b32_e32 v75, v2
	v_mov_b32_e32 v76, v2
	v_mov_b32_e32 v77, v2
	v_mov_b32_e32 v78, v2
	v_mov_b32_e32 v79, v2
	v_mov_b32_e32 v80, v2
	v_mov_b32_e32 v81, v2
	v_mov_b32_e32 v90, v2
	v_mov_b32_e32 v91, v2
	v_mov_b32_e32 v92, v2
	v_mov_b32_e32 v93, v2
	v_mov_b32_e32 v94, v2
	v_mov_b32_e32 v95, v2
	v_mov_b32_e32 v96, v2
	v_mov_b32_e32 v97, v2
	v_mov_b32_e32 v106, v2
	v_mov_b32_e32 v107, v2
	v_mov_b32_e32 v108, v2
	v_mov_b32_e32 v109, v2
	v_mov_b32_e32 v110, v2
	v_mov_b32_e32 v111, v2
	v_mov_b32_e32 v112, v2
	v_mov_b32_e32 v113, v2
	v_mov_b32_e32 v122, v2
	v_mov_b32_e32 v123, v2
	v_mov_b32_e32 v124, v2
	v_mov_b32_e32 v125, v2
	v_mov_b32_e32 v126, v2
	v_mov_b32_e32 v127, v2
	v_mov_b32_e32 v128, v2
	v_mov_b32_e32 v129, v2
.LBB0_341:
	s_add_u32 s14, s12, 0xfff00080
	s_addc_u32 s15, s13, -1
	s_cmp_eq_u32 s39, 60
	s_cselect_b32 s17, s51, s15
	s_cselect_b32 s16, s50, s14
	s_cselect_b32 s15, s53, s1
	s_cselect_b32 s14, s52, s0
	s_cmp_lt_i32 s39, 57
	s_cselect_b32 s100, 0x100, 0
	s_mov_b32 s101, 0
	v_lshl_add_u64 v[242:243], v[242:243], 0, s[100:101]
	s_add_i32 m0, s8, 0xc000
	ds_read_b128 v[152:155], v252
	ds_read_b128 v[162:165], v252 offset:1024
	global_load_lds_dwordx4 v148, s[12:13]
	s_add_i32 m0, s8, 0xe000
	ds_read_b128 v[166:169], v252 offset:2048
	ds_read_b128 v[170:173], v252 offset:3072
	global_load_lds_dwordx4 v150, s[12:13]
	ds_read_b128 v[174:177], v252 offset:16384
	ds_read_b128 v[182:185], v252 offset:17408
	ds_read_b128 v[186:189], v252 offset:18432
	ds_read_b128 v[190:193], v252 offset:19456
	ds_read_b128 v[194:197], v161
	ds_read_b128 v[198:201], v161 offset:1024
	ds_read_b128 v[202:205], v161 offset:2048
	ds_read_b128 v[206:209], v161 offset:3072
	ds_read_b128 v[210:213], v161 offset:4096
	ds_read_b128 v[214:217], v161 offset:5120
	ds_read_b128 v[218:221], v161 offset:6144
	ds_read_b128 v[222:225], v161 offset:7168
	s_waitcnt vmcnt(8)
	s_mov_b32 m0, 0x21800
	s_mov_b64 exec, 0xff
	s_waitcnt lgkmcnt(0)
	global_load_lds_dword v[242:243], off
	s_mov_b64 exec, -1
	s_barrier
	v_mfma_f32_16x16x32_bf16 v[126:129], v[152:155], v[194:197], v[126:129]
	v_mfma_f32_16x16x32_bf16 v[126:129], v[162:165], v[198:201], v[126:129]
	v_mfma_f32_16x16x32_bf16 v[122:125], v[166:169], v[194:197], v[122:125]
	v_mfma_f32_16x16x32_bf16 v[122:125], v[170:173], v[198:201], v[122:125]
	v_mfma_f32_16x16x32_bf16 v[110:113], v[152:155], v[202:205], v[110:113]
	v_mfma_f32_16x16x32_bf16 v[110:113], v[162:165], v[206:209], v[110:113]
	v_mfma_f32_16x16x32_bf16 v[106:109], v[166:169], v[202:205], v[106:109]
	v_mfma_f32_16x16x32_bf16 v[106:109], v[170:173], v[206:209], v[106:109]
	v_mfma_f32_16x16x32_bf16 v[94:97], v[152:155], v[210:213], v[94:97]
	v_mfma_f32_16x16x32_bf16 v[94:97], v[162:165], v[214:217], v[94:97]
	v_mfma_f32_16x16x32_bf16 v[90:93], v[166:169], v[210:213], v[90:93]
	v_mfma_f32_16x16x32_bf16 v[90:93], v[170:173], v[214:217], v[90:93]
	v_mfma_f32_16x16x32_bf16 v[78:81], v[152:155], v[218:221], v[78:81]
	v_mfma_f32_16x16x32_bf16 v[78:81], v[162:165], v[222:225], v[78:81]
	v_mfma_f32_16x16x32_bf16 v[74:77], v[166:169], v[218:221], v[74:77]
	v_mfma_f32_16x16x32_bf16 v[74:77], v[170:173], v[222:225], v[74:77]
	v_mfma_f32_16x16x32_bf16 v[118:121], v[174:177], v[194:197], v[118:121]
	v_mfma_f32_16x16x32_bf16 v[118:121], v[182:185], v[198:201], v[118:121]
	v_mfma_f32_16x16x32_bf16 v[114:117], v[186:189], v[194:197], v[114:117]
	v_mfma_f32_16x16x32_bf16 v[114:117], v[190:193], v[198:201], v[114:117]
	v_mfma_f32_16x16x32_bf16 v[102:105], v[174:177], v[202:205], v[102:105]
	v_mfma_f32_16x16x32_bf16 v[102:105], v[182:185], v[206:209], v[102:105]
	v_mfma_f32_16x16x32_bf16 v[98:101], v[186:189], v[202:205], v[98:101]
	v_mfma_f32_16x16x32_bf16 v[98:101], v[190:193], v[206:209], v[98:101]
	v_mfma_f32_16x16x32_bf16 v[86:89], v[174:177], v[210:213], v[86:89]
	v_mfma_f32_16x16x32_bf16 v[86:89], v[182:185], v[214:217], v[86:89]
	v_mfma_f32_16x16x32_bf16 v[82:85], v[186:189], v[210:213], v[82:85]
	v_mfma_f32_16x16x32_bf16 v[82:85], v[190:193], v[214:217], v[82:85]
	v_mfma_f32_16x16x32_bf16 v[70:73], v[174:177], v[218:221], v[70:73]
	v_mfma_f32_16x16x32_bf16 v[70:73], v[182:185], v[222:225], v[70:73]
	v_mfma_f32_16x16x32_bf16 v[66:69], v[186:189], v[218:221], v[66:69]
	v_mfma_f32_16x16x32_bf16 v[66:69], v[190:193], v[222:225], v[66:69]
	s_barrier
	s_add_i32 m0, s28, 0x10000
	ds_read_b128 v[194:197], v161 offset:16384
	ds_read_b128 v[198:201], v161 offset:17408
	global_load_lds_dwordx4 v144, s[14:15]
	s_add_i32 m0, s28, 0x12000
	s_add_u32 s98, s14, 0x100000
	s_addc_u32 s99, s15, 0
	ds_read_b128 v[202:205], v161 offset:18432
	global_load_lds_dwordx4 v140, s[14:15]
	s_add_i32 m0, s28, 0x14000
	ds_read_b128 v[206:209], v161 offset:19456
	ds_read_b128 v[210:213], v161 offset:20480
	global_load_lds_dwordx4 v144, s[98:99]
	s_add_i32 m0, s28, 0x16000
	ds_read_b128 v[214:217], v161 offset:21504
	ds_read_b128 v[218:221], v161 offset:22528
	global_load_lds_dwordx4 v140, s[98:99]
	s_mov_b32 m0, s8
	ds_read_b128 v[222:225], v161 offset:23552
	global_load_lds_dwordx4 v146, s[16:17]
	s_mov_b32 m0, s9
	s_nop 0
	global_load_lds_dwordx4 v142, s[16:17]
	s_waitcnt vmcnt(9)
	s_waitcnt lgkmcnt(0)
	s_barrier
	v_mfma_f32_16x16x32_bf16 v[62:65], v[152:155], v[194:197], v[62:65]
	v_mfma_f32_16x16x32_bf16 v[62:65], v[162:165], v[198:201], v[62:65]
	v_mfma_f32_16x16x32_bf16 v[58:61], v[166:169], v[194:197], v[58:61]
	v_mfma_f32_16x16x32_bf16 v[58:61], v[170:173], v[198:201], v[58:61]
	v_mfma_f32_16x16x32_bf16 v[46:49], v[152:155], v[202:205], v[46:49]
	v_mfma_f32_16x16x32_bf16 v[46:49], v[162:165], v[206:209], v[46:49]
	v_mfma_f32_16x16x32_bf16 v[42:45], v[166:169], v[202:205], v[42:45]
	v_mfma_f32_16x16x32_bf16 v[42:45], v[170:173], v[206:209], v[42:45]
	v_mfma_f32_16x16x32_bf16 v[30:33], v[152:155], v[210:213], v[30:33]
	v_mfma_f32_16x16x32_bf16 v[30:33], v[162:165], v[214:217], v[30:33]
	v_mfma_f32_16x16x32_bf16 v[26:29], v[166:169], v[210:213], v[26:29]
	v_mfma_f32_16x16x32_bf16 v[26:29], v[170:173], v[214:217], v[26:29]
	v_mfma_f32_16x16x32_bf16 v[14:17], v[152:155], v[218:221], v[14:17]
	v_mfma_f32_16x16x32_bf16 v[14:17], v[162:165], v[222:225], v[14:17]
	v_mfma_f32_16x16x32_bf16 v[10:13], v[166:169], v[218:221], v[10:13]
	v_mfma_f32_16x16x32_bf16 v[10:13], v[170:173], v[222:225], v[10:13]
	v_mfma_f32_16x16x32_bf16 v[54:57], v[174:177], v[194:197], v[54:57]
	v_mfma_f32_16x16x32_bf16 v[54:57], v[182:185], v[198:201], v[54:57]
	v_mfma_f32_16x16x32_bf16 v[50:53], v[186:189], v[194:197], v[50:53]
	v_mfma_f32_16x16x32_bf16 v[50:53], v[190:193], v[198:201], v[50:53]
	v_mfma_f32_16x16x32_bf16 v[38:41], v[174:177], v[202:205], v[38:41]
	v_mfma_f32_16x16x32_bf16 v[38:41], v[182:185], v[206:209], v[38:41]
	v_mfma_f32_16x16x32_bf16 v[34:37], v[186:189], v[202:205], v[34:37]
	v_mfma_f32_16x16x32_bf16 v[34:37], v[190:193], v[206:209], v[34:37]
	v_mfma_f32_16x16x32_bf16 v[22:25], v[174:177], v[210:213], v[22:25]
	v_mfma_f32_16x16x32_bf16 v[22:25], v[182:185], v[214:217], v[22:25]
	v_mfma_f32_16x16x32_bf16 v[18:21], v[186:189], v[210:213], v[18:21]
	v_mfma_f32_16x16x32_bf16 v[18:21], v[190:193], v[214:217], v[18:21]
	v_mfma_f32_16x16x32_bf16 v[6:9], v[174:177], v[218:221], v[6:9]
	v_mfma_f32_16x16x32_bf16 v[6:9], v[182:185], v[222:225], v[6:9]
	v_mfma_f32_16x16x32_bf16 v[2:5], v[186:189], v[218:221], v[2:5]
	v_mfma_f32_16x16x32_bf16 v[2:5], v[190:193], v[222:225], v[2:5]
	s_barrier
	s_add_u32 s100, s16, 0x100000
	s_addc_u32 s101, s17, 0
	s_mov_b32 m0, s29
	ds_read_b128 v[152:155], v252 offset:32768
	ds_read_b128 v[162:165], v252 offset:33792
	global_load_lds_dwordx4 v146, s[100:101]
	s_mov_b32 m0, s36
	ds_read_b128 v[166:169], v252 offset:34816
	ds_read_b128 v[170:173], v252 offset:35840
	global_load_lds_dwordx4 v142, s[100:101]
	ds_read_b128 v[174:177], v252 offset:49152
	ds_read_b128 v[182:185], v252 offset:50176
	ds_read_b128 v[186:189], v252 offset:51200
	ds_read_b128 v[190:193], v252 offset:52224
	ds_read_b128 v[194:197], v161 offset:32768
	ds_read_b128 v[198:201], v161 offset:33792
	ds_read_b128 v[202:205], v161 offset:34816
	ds_read_b128 v[206:209], v161 offset:35840
	ds_read_b128 v[210:213], v161 offset:36864
	ds_read_b128 v[214:217], v161 offset:37888
	ds_read_b128 v[218:221], v161 offset:38912
	ds_read_b128 v[222:225], v161 offset:39936
	s_waitcnt vmcnt(9)
	s_waitcnt lgkmcnt(0)
	s_barrier
	v_mfma_f32_16x16x32_bf16 v[126:129], v[152:155], v[194:197], v[126:129]
	v_mfma_f32_16x16x32_bf16 v[126:129], v[162:165], v[198:201], v[126:129]
	v_mfma_f32_16x16x32_bf16 v[122:125], v[166:169], v[194:197], v[122:125]
	v_mfma_f32_16x16x32_bf16 v[122:125], v[170:173], v[198:201], v[122:125]
	v_mfma_f32_16x16x32_bf16 v[110:113], v[152:155], v[202:205], v[110:113]
	v_mfma_f32_16x16x32_bf16 v[110:113], v[162:165], v[206:209], v[110:113]
	v_mfma_f32_16x16x32_bf16 v[106:109], v[166:169], v[202:205], v[106:109]
	v_mfma_f32_16x16x32_bf16 v[106:109], v[170:173], v[206:209], v[106:109]
	v_mfma_f32_16x16x32_bf16 v[94:97], v[152:155], v[210:213], v[94:97]
	v_mfma_f32_16x16x32_bf16 v[94:97], v[162:165], v[214:217], v[94:97]
	v_mfma_f32_16x16x32_bf16 v[90:93], v[166:169], v[210:213], v[90:93]
	v_mfma_f32_16x16x32_bf16 v[90:93], v[170:173], v[214:217], v[90:93]
	v_mfma_f32_16x16x32_bf16 v[78:81], v[152:155], v[218:221], v[78:81]
	v_mfma_f32_16x16x32_bf16 v[78:81], v[162:165], v[222:225], v[78:81]
	v_mfma_f32_16x16x32_bf16 v[74:77], v[166:169], v[218:221], v[74:77]
	v_mfma_f32_16x16x32_bf16 v[74:77], v[170:173], v[222:225], v[74:77]
	v_mfma_f32_16x16x32_bf16 v[118:121], v[174:177], v[194:197], v[118:121]
	v_mfma_f32_16x16x32_bf16 v[118:121], v[182:185], v[198:201], v[118:121]
	v_mfma_f32_16x16x32_bf16 v[114:117], v[186:189], v[194:197], v[114:117]
	v_mfma_f32_16x16x32_bf16 v[114:117], v[190:193], v[198:201], v[114:117]
	v_mfma_f32_16x16x32_bf16 v[102:105], v[174:177], v[202:205], v[102:105]
	v_mfma_f32_16x16x32_bf16 v[102:105], v[182:185], v[206:209], v[102:105]
	v_mfma_f32_16x16x32_bf16 v[98:101], v[186:189], v[202:205], v[98:101]
	v_mfma_f32_16x16x32_bf16 v[98:101], v[190:193], v[206:209], v[98:101]
	v_mfma_f32_16x16x32_bf16 v[86:89], v[174:177], v[210:213], v[86:89]
	v_mfma_f32_16x16x32_bf16 v[86:89], v[182:185], v[214:217], v[86:89]
	v_mfma_f32_16x16x32_bf16 v[82:85], v[186:189], v[210:213], v[82:85]
	v_mfma_f32_16x16x32_bf16 v[82:85], v[190:193], v[214:217], v[82:85]
	v_mfma_f32_16x16x32_bf16 v[70:73], v[174:177], v[218:221], v[70:73]
	v_mfma_f32_16x16x32_bf16 v[70:73], v[182:185], v[222:225], v[70:73]
	v_mfma_f32_16x16x32_bf16 v[66:69], v[186:189], v[218:221], v[66:69]
	v_mfma_f32_16x16x32_bf16 v[66:69], v[190:193], v[222:225], v[66:69]
	s_barrier
	s_add_u32 s14, s14, 0x80
	s_addc_u32 s15, s15, 0
	s_add_i32 m0, s28, 0x18000
	ds_read_b128 v[194:197], v161 offset:49152
	ds_read_b128 v[198:201], v161 offset:50176
	global_load_lds_dwordx4 v144, s[14:15]
	s_add_i32 m0, s28, 0x1a000
	s_add_u32 s98, s98, 0x80
	s_addc_u32 s99, s99, 0
	ds_read_b128 v[202:205], v161 offset:51200
	global_load_lds_dwordx4 v140, s[14:15]
	s_add_i32 m0, s28, 0x1c000
	ds_read_b128 v[206:209], v161 offset:52224
	ds_read_b128 v[210:213], v161 offset:53248
	global_load_lds_dwordx4 v144, s[98:99]
	s_add_i32 m0, s28, 0x1e000
	s_add_u32 s16, s16, 0x80
	s_addc_u32 s17, s17, 0
	ds_read_b128 v[214:217], v161 offset:54272
	ds_read_b128 v[218:221], v161 offset:55296
	global_load_lds_dwordx4 v140, s[98:99]
	s_mov_b32 m0, s45
	ds_read_b128 v[222:225], v161 offset:56320
	global_load_lds_dwordx4 v146, s[16:17]
	s_mov_b32 m0, s46
	s_nop 0
	global_load_lds_dwordx4 v142, s[16:17]
	s_waitcnt vmcnt(8)
	s_waitcnt lgkmcnt(0)
	s_barrier
	v_mfma_f32_16x16x32_bf16 v[62:65], v[152:155], v[194:197], v[62:65]
	v_mfma_f32_16x16x32_bf16 v[62:65], v[162:165], v[198:201], v[62:65]
	v_mfma_f32_16x16x32_bf16 v[58:61], v[166:169], v[194:197], v[58:61]
	v_mfma_f32_16x16x32_bf16 v[58:61], v[170:173], v[198:201], v[58:61]
	v_mfma_f32_16x16x32_bf16 v[46:49], v[152:155], v[202:205], v[46:49]
	v_mfma_f32_16x16x32_bf16 v[46:49], v[162:165], v[206:209], v[46:49]
	v_mfma_f32_16x16x32_bf16 v[42:45], v[166:169], v[202:205], v[42:45]
	v_mfma_f32_16x16x32_bf16 v[42:45], v[170:173], v[206:209], v[42:45]
	v_mfma_f32_16x16x32_bf16 v[30:33], v[152:155], v[210:213], v[30:33]
	v_mfma_f32_16x16x32_bf16 v[30:33], v[162:165], v[214:217], v[30:33]
	v_mfma_f32_16x16x32_bf16 v[26:29], v[166:169], v[210:213], v[26:29]
	v_mfma_f32_16x16x32_bf16 v[26:29], v[170:173], v[214:217], v[26:29]
	v_mfma_f32_16x16x32_bf16 v[14:17], v[152:155], v[218:221], v[14:17]
	v_mfma_f32_16x16x32_bf16 v[14:17], v[162:165], v[222:225], v[14:17]
	v_mfma_f32_16x16x32_bf16 v[10:13], v[166:169], v[218:221], v[10:13]
	v_mfma_f32_16x16x32_bf16 v[10:13], v[170:173], v[222:225], v[10:13]
	v_mfma_f32_16x16x32_bf16 v[54:57], v[174:177], v[194:197], v[54:57]
	v_mfma_f32_16x16x32_bf16 v[54:57], v[182:185], v[198:201], v[54:57]
	v_mfma_f32_16x16x32_bf16 v[50:53], v[186:189], v[194:197], v[50:53]
	v_mfma_f32_16x16x32_bf16 v[50:53], v[190:193], v[198:201], v[50:53]
	v_mfma_f32_16x16x32_bf16 v[38:41], v[174:177], v[202:205], v[38:41]
	v_mfma_f32_16x16x32_bf16 v[38:41], v[182:185], v[206:209], v[38:41]
	v_mfma_f32_16x16x32_bf16 v[34:37], v[186:189], v[202:205], v[34:37]
	v_mfma_f32_16x16x32_bf16 v[34:37], v[190:193], v[206:209], v[34:37]
	v_mfma_f32_16x16x32_bf16 v[22:25], v[174:177], v[210:213], v[22:25]
	v_mfma_f32_16x16x32_bf16 v[22:25], v[182:185], v[214:217], v[22:25]
	v_mfma_f32_16x16x32_bf16 v[18:21], v[186:189], v[210:213], v[18:21]
	v_mfma_f32_16x16x32_bf16 v[18:21], v[190:193], v[214:217], v[18:21]
	v_mfma_f32_16x16x32_bf16 v[6:9], v[174:177], v[218:221], v[6:9]
	v_mfma_f32_16x16x32_bf16 v[6:9], v[182:185], v[222:225], v[6:9]
	v_mfma_f32_16x16x32_bf16 v[2:5], v[186:189], v[218:221], v[2:5]
	v_mfma_f32_16x16x32_bf16 v[2:5], v[190:193], v[222:225], v[2:5]
	s_barrier
	s_add_i32 s39, s39, 2
	s_add_u32 s12, s12, 0x100
	s_addc_u32 s13, s13, 0
	s_add_u32 s0, s0, 0x100
	s_addc_u32 s1, s1, 0
	s_cmp_gt_u32 s39, 61
	s_cbranch_scc0 .LBB0_341
	s_and_b64 vcc, exec, s[34:35]
	s_cbranch_vccz .LBB0_344
	s_barrier

.LBB0_571:
	s_and_b32 s98, s47, 3
	s_and_b32 s99, s46, 7
	s_lshl_b32 s98, s98, 6
	s_lshl_b32 s99, s99, 5
	v_and_b32_e32 v244, 63, v0
	v_and_b32_e32 v244, 7, v244
	v_lshrrev_b32_e32 v245, 6, v0
	v_lshl_add_u32 v244, v245, 3, v244
	v_add_u32_e32 v244, 0x80, v244
	v_cmp_gt_u32_e32 vcc, 0x80, v244
	v_and_b32_e32 v245, 63, v244
	v_add_u32_e32 v245, s98, v245
	v_lshrrev_b32_e32 v246, 6, v244
	v_subrev_u32_e32 v247, 0x80, v244
	v_and_b32_e32 v248, 31, v247
	v_add_u32_e32 v248, s99, v248
	v_lshrrev_b32_e32 v247, 5, v247
	v_cndmask_b32_e32 v245, v248, v245, vcc
	v_cndmask_b32_e32 v246, v247, v246, vcc
	v_lshlrev_b32_e32 v245, 13, v245
	v_lshl_add_u32 v245, v246, 7, v245
	v_add_u32_e32 v244, 0x80, v245
	v_mov_b32_e32 v245, 0
	v_mov_b32_e32 v246, s12
	v_mov_b32_e32 v247, s13
	v_mov_b32_e32 v248, s14
	v_mov_b32_e32 v249, s15
	v_cndmask_b32_e32 v246, v248, v246, vcc
	v_cndmask_b32_e32 v247, v249, v247, vcc
	v_lshl_add_u64 v[242:243], v[246:247], 0, v[244:245]
	v_add_u32_e32 v252, 0x10000, v159
	s_add_u32 s12, s12, 0x100080
	s_addc_u32 s13, s13, 0
	s_add_u32 s0, s14, 0x100
	v_mov_b32_e32 v2, 0
	s_addc_u32 s1, s15, 0
	s_mov_b32 s35, -2
	v_mov_b32_e32 v3, v2
	v_mov_b32_e32 v4, v2
	v_mov_b32_e32 v5, v2
	v_mov_b32_e32 v6, v2
	v_mov_b32_e32 v7, v2
	v_mov_b32_e32 v8, v2
	v_mov_b32_e32 v9, v2
	v_mov_b32_e32 v18, v2
	v_mov_b32_e32 v19, v2
	v_mov_b32_e32 v20, v2
	v_mov_b32_e32 v21, v2
	v_mov_b32_e32 v22, v2
	v_mov_b32_e32 v23, v2
	v_mov_b32_e32 v24, v2
	v_mov_b32_e32 v25, v2
	v_mov_b32_e32 v34, v2
	v_mov_b32_e32 v35, v2
	v_mov_b32_e32 v36, v2
	v_mov_b32_e32 v37, v2
	v_mov_b32_e32 v38, v2
	v_mov_b32_e32 v39, v2
	v_mov_b32_e32 v40, v2
	v_mov_b32_e32 v41, v2
	v_mov_b32_e32 v50, v2
	v_mov_b32_e32 v51, v2
	v_mov_b32_e32 v52, v2
	v_mov_b32_e32 v53, v2
	v_mov_b32_e32 v54, v2
	v_mov_b32_e32 v55, v2
	v_mov_b32_e32 v56, v2
	v_mov_b32_e32 v57, v2
	v_mov_b32_e32 v10, v2
	v_mov_b32_e32 v11, v2
	v_mov_b32_e32 v12, v2
	v_mov_b32_e32 v13, v2
	v_mov_b32_e32 v14, v2
	v_mov_b32_e32 v15, v2
	v_mov_b32_e32 v16, v2
	v_mov_b32_e32 v17, v2
	v_mov_b32_e32 v26, v2
	v_mov_b32_e32 v27, v2
	v_mov_b32_e32 v28, v2
	v_mov_b32_e32 v29, v2
	v_mov_b32_e32 v30, v2
	v_mov_b32_e32 v31, v2
	v_mov_b32_e32 v32, v2
	v_mov_b32_e32 v33, v2
	v_mov_b32_e32 v42, v2
	v_mov_b32_e32 v43, v2
	v_mov_b32_e32 v44, v2
	v_mov_b32_e32 v45, v2
	v_mov_b32_e32 v46, v2
	v_mov_b32_e32 v47, v2
	v_mov_b32_e32 v48, v2
	v_mov_b32_e32 v49, v2
	v_mov_b32_e32 v58, v2
	v_mov_b32_e32 v59, v2
	v_mov_b32_e32 v60, v2
	v_mov_b32_e32 v61, v2
	v_mov_b32_e32 v62, v2
	v_mov_b32_e32 v63, v2
	v_mov_b32_e32 v64, v2
	v_mov_b32_e32 v65, v2
	v_mov_b32_e32 v66, v2
	v_mov_b32_e32 v67, v2
	v_mov_b32_e32 v68, v2
	v_mov_b32_e32 v69, v2
	v_mov_b32_e32 v70, v2
	v_mov_b32_e32 v71, v2
	v_mov_b32_e32 v72, v2
	v_mov_b32_e32 v73, v2
	v_mov_b32_e32 v82, v2
	v_mov_b32_e32 v83, v2
	v_mov_b32_e32 v84, v2
	v_mov_b32_e32 v85, v2
	v_mov_b32_e32 v86, v2
	v_mov_b32_e32 v87, v2
	v_mov_b32_e32 v88, v2
	v_mov_b32_e32 v89, v2
	v_mov_b32_e32 v98, v2
	v_mov_b32_e32 v99, v2
	v_mov_b32_e32 v100, v2
	v_mov_b32_e32 v101, v2
	v_mov_b32_e32 v102, v2
	v_mov_b32_e32 v103, v2
	v_mov_b32_e32 v104, v2
	v_mov_b32_e32 v105, v2
	v_mov_b32_e32 v114, v2
	v_mov_b32_e32 v115, v2
	v_mov_b32_e32 v116, v2
	v_mov_b32_e32 v117, v2
	v_mov_b32_e32 v118, v2
	v_mov_b32_e32 v119, v2
	v_mov_b32_e32 v120, v2
	v_mov_b32_e32 v121, v2
	v_mov_b32_e32 v74, v2
	v_mov_b32_e32 v75, v2
	v_mov_b32_e32 v76, v2
	v_mov_b32_e32 v77, v2
	v_mov_b32_e32 v78, v2
	v_mov_b32_e32 v79, v2
	v_mov_b32_e32 v80, v2
	v_mov_b32_e32 v81, v2
	v_mov_b32_e32 v90, v2
	v_mov_b32_e32 v91, v2
	v_mov_b32_e32 v92, v2
	v_mov_b32_e32 v93, v2
	v_mov_b32_e32 v94, v2
	v_mov_b32_e32 v95, v2
	v_mov_b32_e32 v96, v2
	v_mov_b32_e32 v97, v2
	v_mov_b32_e32 v106, v2
	v_mov_b32_e32 v107, v2
	v_mov_b32_e32 v108, v2
	v_mov_b32_e32 v109, v2
	v_mov_b32_e32 v110, v2
	v_mov_b32_e32 v111, v2
	v_mov_b32_e32 v112, v2
	v_mov_b32_e32 v113, v2
	v_mov_b32_e32 v122, v2
	v_mov_b32_e32 v123, v2
	v_mov_b32_e32 v124, v2
	v_mov_b32_e32 v125, v2
	v_mov_b32_e32 v126, v2
	v_mov_b32_e32 v127, v2
	v_mov_b32_e32 v128, v2
	v_mov_b32_e32 v129, v2
.LBB0_572:
	s_add_u32 s14, s12, 0xfff00080
	s_addc_u32 s15, s13, -1
	s_cmp_eq_u32 s35, 60
	s_cselect_b32 s17, s51, s15
	s_cselect_b32 s16, s50, s14
	s_cselect_b32 s15, s53, s1
	s_cselect_b32 s14, s52, s0
	s_cmp_lt_i32 s35, 57
	s_cselect_b32 s100, 0x100, 0
	s_mov_b32 s101, 0
	v_lshl_add_u64 v[242:243], v[242:243], 0, s[100:101]
	s_add_i32 m0, s8, 0xc000
	ds_read_b128 v[152:155], v252
	ds_read_b128 v[162:165], v252 offset:1024
	global_load_lds_dwordx4 v148, s[12:13]
	s_add_i32 m0, s8, 0xe000
	ds_read_b128 v[166:169], v252 offset:2048
	ds_read_b128 v[170:173], v252 offset:3072
	global_load_lds_dwordx4 v150, s[12:13]
	ds_read_b128 v[174:177], v252 offset:16384
	ds_read_b128 v[182:185], v252 offset:17408
	ds_read_b128 v[186:189], v252 offset:18432
	ds_read_b128 v[190:193], v252 offset:19456
	ds_read_b128 v[194:197], v161
	ds_read_b128 v[198:201], v161 offset:1024
	ds_read_b128 v[202:205], v161 offset:2048
	ds_read_b128 v[206:209], v161 offset:3072
	ds_read_b128 v[210:213], v161 offset:4096
	ds_read_b128 v[214:217], v161 offset:5120
	ds_read_b128 v[218:221], v161 offset:6144
	ds_read_b128 v[222:225], v161 offset:7168
	s_waitcnt vmcnt(8)
	s_mov_b32 m0, 0x21800
	s_mov_b64 exec, 0xff
	s_waitcnt lgkmcnt(0)
	global_load_lds_dword v[242:243], off
	s_mov_b64 exec, -1
	s_barrier
	v_mfma_f32_16x16x32_bf16 v[126:129], v[152:155], v[194:197], v[126:129]
	v_mfma_f32_16x16x32_bf16 v[126:129], v[162:165], v[198:201], v[126:129]
	v_mfma_f32_16x16x32_bf16 v[122:125], v[166:169], v[194:197], v[122:125]
	v_mfma_f32_16x16x32_bf16 v[122:125], v[170:173], v[198:201], v[122:125]
	v_mfma_f32_16x16x32_bf16 v[110:113], v[152:155], v[202:205], v[110:113]
	v_mfma_f32_16x16x32_bf16 v[110:113], v[162:165], v[206:209], v[110:113]
	v_mfma_f32_16x16x32_bf16 v[106:109], v[166:169], v[202:205], v[106:109]
	v_mfma_f32_16x16x32_bf16 v[106:109], v[170:173], v[206:209], v[106:109]
	v_mfma_f32_16x16x32_bf16 v[94:97], v[152:155], v[210:213], v[94:97]
	v_mfma_f32_16x16x32_bf16 v[94:97], v[162:165], v[214:217], v[94:97]
	v_mfma_f32_16x16x32_bf16 v[90:93], v[166:169], v[210:213], v[90:93]
	v_mfma_f32_16x16x32_bf16 v[90:93], v[170:173], v[214:217], v[90:93]
	v_mfma_f32_16x16x32_bf16 v[78:81], v[152:155], v[218:221], v[78:81]
	v_mfma_f32_16x16x32_bf16 v[78:81], v[162:165], v[222:225], v[78:81]
	v_mfma_f32_16x16x32_bf16 v[74:77], v[166:169], v[218:221], v[74:77]
	v_mfma_f32_16x16x32_bf16 v[74:77], v[170:173], v[222:225], v[74:77]
	v_mfma_f32_16x16x32_bf16 v[118:121], v[174:177], v[194:197], v[118:121]
	v_mfma_f32_16x16x32_bf16 v[118:121], v[182:185], v[198:201], v[118:121]
	v_mfma_f32_16x16x32_bf16 v[114:117], v[186:189], v[194:197], v[114:117]
	v_mfma_f32_16x16x32_bf16 v[114:117], v[190:193], v[198:201], v[114:117]
	v_mfma_f32_16x16x32_bf16 v[102:105], v[174:177], v[202:205], v[102:105]
	v_mfma_f32_16x16x32_bf16 v[102:105], v[182:185], v[206:209], v[102:105]
	v_mfma_f32_16x16x32_bf16 v[98:101], v[186:189], v[202:205], v[98:101]
	v_mfma_f32_16x16x32_bf16 v[98:101], v[190:193], v[206:209], v[98:101]
	v_mfma_f32_16x16x32_bf16 v[86:89], v[174:177], v[210:213], v[86:89]
	v_mfma_f32_16x16x32_bf16 v[86:89], v[182:185], v[214:217], v[86:89]
	v_mfma_f32_16x16x32_bf16 v[82:85], v[186:189], v[210:213], v[82:85]
	v_mfma_f32_16x16x32_bf16 v[82:85], v[190:193], v[214:217], v[82:85]
	v_mfma_f32_16x16x32_bf16 v[70:73], v[174:177], v[218:221], v[70:73]
	v_mfma_f32_16x16x32_bf16 v[70:73], v[182:185], v[222:225], v[70:73]
	v_mfma_f32_16x16x32_bf16 v[66:69], v[186:189], v[218:221], v[66:69]
	v_mfma_f32_16x16x32_bf16 v[66:69], v[190:193], v[222:225], v[66:69]
	s_barrier
	s_add_i32 m0, s28, 0x10000
	ds_read_b128 v[194:197], v161 offset:16384
	ds_read_b128 v[198:201], v161 offset:17408
	global_load_lds_dwordx4 v144, s[14:15]
	s_add_i32 m0, s28, 0x12000
	s_add_u32 s98, s14, 0x100000
	s_addc_u32 s99, s15, 0
	ds_read_b128 v[202:205], v161 offset:18432
	global_load_lds_dwordx4 v140, s[14:15]
	s_add_i32 m0, s28, 0x14000
	ds_read_b128 v[206:209], v161 offset:19456
	ds_read_b128 v[210:213], v161 offset:20480
	global_load_lds_dwordx4 v144, s[98:99]
	s_add_i32 m0, s28, 0x16000
	ds_read_b128 v[214:217], v161 offset:21504
	ds_read_b128 v[218:221], v161 offset:22528
	global_load_lds_dwordx4 v140, s[98:99]
	s_mov_b32 m0, s8
	ds_read_b128 v[222:225], v161 offset:23552
	global_load_lds_dwordx4 v146, s[16:17]
	s_mov_b32 m0, s9
	s_nop 0
	global_load_lds_dwordx4 v142, s[16:17]
	s_waitcnt vmcnt(9)
	s_waitcnt lgkmcnt(0)
	s_barrier
	v_mfma_f32_16x16x32_bf16 v[62:65], v[152:155], v[194:197], v[62:65]
	v_mfma_f32_16x16x32_bf16 v[62:65], v[162:165], v[198:201], v[62:65]
	v_mfma_f32_16x16x32_bf16 v[58:61], v[166:169], v[194:197], v[58:61]
	v_mfma_f32_16x16x32_bf16 v[58:61], v[170:173], v[198:201], v[58:61]
	v_mfma_f32_16x16x32_bf16 v[46:49], v[152:155], v[202:205], v[46:49]
	v_mfma_f32_16x16x32_bf16 v[46:49], v[162:165], v[206:209], v[46:49]
	v_mfma_f32_16x16x32_bf16 v[42:45], v[166:169], v[202:205], v[42:45]
	v_mfma_f32_16x16x32_bf16 v[42:45], v[170:173], v[206:209], v[42:45]
	v_mfma_f32_16x16x32_bf16 v[30:33], v[152:155], v[210:213], v[30:33]
	v_mfma_f32_16x16x32_bf16 v[30:33], v[162:165], v[214:217], v[30:33]
	v_mfma_f32_16x16x32_bf16 v[26:29], v[166:169], v[210:213], v[26:29]
	v_mfma_f32_16x16x32_bf16 v[26:29], v[170:173], v[214:217], v[26:29]
	v_mfma_f32_16x16x32_bf16 v[14:17], v[152:155], v[218:221], v[14:17]
	v_mfma_f32_16x16x32_bf16 v[14:17], v[162:165], v[222:225], v[14:17]
	v_mfma_f32_16x16x32_bf16 v[10:13], v[166:169], v[218:221], v[10:13]
	v_mfma_f32_16x16x32_bf16 v[10:13], v[170:173], v[222:225], v[10:13]
	v_mfma_f32_16x16x32_bf16 v[54:57], v[174:177], v[194:197], v[54:57]
	v_mfma_f32_16x16x32_bf16 v[54:57], v[182:185], v[198:201], v[54:57]
	v_mfma_f32_16x16x32_bf16 v[50:53], v[186:189], v[194:197], v[50:53]
	v_mfma_f32_16x16x32_bf16 v[50:53], v[190:193], v[198:201], v[50:53]
	v_mfma_f32_16x16x32_bf16 v[38:41], v[174:177], v[202:205], v[38:41]
	v_mfma_f32_16x16x32_bf16 v[38:41], v[182:185], v[206:209], v[38:41]
	v_mfma_f32_16x16x32_bf16 v[34:37], v[186:189], v[202:205], v[34:37]
	v_mfma_f32_16x16x32_bf16 v[34:37], v[190:193], v[206:209], v[34:37]
	v_mfma_f32_16x16x32_bf16 v[22:25], v[174:177], v[210:213], v[22:25]
	v_mfma_f32_16x16x32_bf16 v[22:25], v[182:185], v[214:217], v[22:25]
	v_mfma_f32_16x16x32_bf16 v[18:21], v[186:189], v[210:213], v[18:21]
	v_mfma_f32_16x16x32_bf16 v[18:21], v[190:193], v[214:217], v[18:21]
	v_mfma_f32_16x16x32_bf16 v[6:9], v[174:177], v[218:221], v[6:9]
	v_mfma_f32_16x16x32_bf16 v[6:9], v[182:185], v[222:225], v[6:9]
	v_mfma_f32_16x16x32_bf16 v[2:5], v[186:189], v[218:221], v[2:5]
	v_mfma_f32_16x16x32_bf16 v[2:5], v[190:193], v[222:225], v[2:5]
	s_barrier
	s_add_u32 s100, s16, 0x100000
	s_addc_u32 s101, s17, 0
	s_mov_b32 m0, s29
	ds_read_b128 v[152:155], v252 offset:32768
	ds_read_b128 v[162:165], v252 offset:33792
	global_load_lds_dwordx4 v146, s[100:101]
	s_mov_b32 m0, s36
	ds_read_b128 v[166:169], v252 offset:34816
	ds_read_b128 v[170:173], v252 offset:35840
	global_load_lds_dwordx4 v142, s[100:101]
	ds_read_b128 v[174:177], v252 offset:49152
	ds_read_b128 v[182:185], v252 offset:50176
	ds_read_b128 v[186:189], v252 offset:51200
	ds_read_b128 v[190:193], v252 offset:52224
	ds_read_b128 v[194:197], v161 offset:32768
	ds_read_b128 v[198:201], v161 offset:33792
	ds_read_b128 v[202:205], v161 offset:34816
	ds_read_b128 v[206:209], v161 offset:35840
	ds_read_b128 v[210:213], v161 offset:36864
	ds_read_b128 v[214:217], v161 offset:37888
	ds_read_b128 v[218:221], v161 offset:38912
	ds_read_b128 v[222:225], v161 offset:39936
	s_waitcnt vmcnt(9)
	s_waitcnt lgkmcnt(0)
	s_barrier
	v_mfma_f32_16x16x32_bf16 v[126:129], v[152:155], v[194:197], v[126:129]
	v_mfma_f32_16x16x32_bf16 v[126:129], v[162:165], v[198:201], v[126:129]
	v_mfma_f32_16x16x32_bf16 v[122:125], v[166:169], v[194:197], v[122:125]
	v_mfma_f32_16x16x32_bf16 v[122:125], v[170:173], v[198:201], v[122:125]
	v_mfma_f32_16x16x32_bf16 v[110:113], v[152:155], v[202:205], v[110:113]
	v_mfma_f32_16x16x32_bf16 v[110:113], v[162:165], v[206:209], v[110:113]
	v_mfma_f32_16x16x32_bf16 v[106:109], v[166:169], v[202:205], v[106:109]
	v_mfma_f32_16x16x32_bf16 v[106:109], v[170:173], v[206:209], v[106:109]
	v_mfma_f32_16x16x32_bf16 v[94:97], v[152:155], v[210:213], v[94:97]
	v_mfma_f32_16x16x32_bf16 v[94:97], v[162:165], v[214:217], v[94:97]
	v_mfma_f32_16x16x32_bf16 v[90:93], v[166:169], v[210:213], v[90:93]
	v_mfma_f32_16x16x32_bf16 v[90:93], v[170:173], v[214:217], v[90:93]
	v_mfma_f32_16x16x32_bf16 v[78:81], v[152:155], v[218:221], v[78:81]
	v_mfma_f32_16x16x32_bf16 v[78:81], v[162:165], v[222:225], v[78:81]
	v_mfma_f32_16x16x32_bf16 v[74:77], v[166:169], v[218:221], v[74:77]
	v_mfma_f32_16x16x32_bf16 v[74:77], v[170:173], v[222:225], v[74:77]
	v_mfma_f32_16x16x32_bf16 v[118:121], v[174:177], v[194:197], v[118:121]
	v_mfma_f32_16x16x32_bf16 v[118:121], v[182:185], v[198:201], v[118:121]
	v_mfma_f32_16x16x32_bf16 v[114:117], v[186:189], v[194:197], v[114:117]
	v_mfma_f32_16x16x32_bf16 v[114:117], v[190:193], v[198:201], v[114:117]
	v_mfma_f32_16x16x32_bf16 v[102:105], v[174:177], v[202:205], v[102:105]
	v_mfma_f32_16x16x32_bf16 v[102:105], v[182:185], v[206:209], v[102:105]
	v_mfma_f32_16x16x32_bf16 v[98:101], v[186:189], v[202:205], v[98:101]
	v_mfma_f32_16x16x32_bf16 v[98:101], v[190:193], v[206:209], v[98:101]
	v_mfma_f32_16x16x32_bf16 v[86:89], v[174:177], v[210:213], v[86:89]
	v_mfma_f32_16x16x32_bf16 v[86:89], v[182:185], v[214:217], v[86:89]
	v_mfma_f32_16x16x32_bf16 v[82:85], v[186:189], v[210:213], v[82:85]
	v_mfma_f32_16x16x32_bf16 v[82:85], v[190:193], v[214:217], v[82:85]
	v_mfma_f32_16x16x32_bf16 v[70:73], v[174:177], v[218:221], v[70:73]
	v_mfma_f32_16x16x32_bf16 v[70:73], v[182:185], v[222:225], v[70:73]
	v_mfma_f32_16x16x32_bf16 v[66:69], v[186:189], v[218:221], v[66:69]
	v_mfma_f32_16x16x32_bf16 v[66:69], v[190:193], v[222:225], v[66:69]
	s_barrier
	s_add_u32 s14, s14, 0x80
	s_addc_u32 s15, s15, 0
	s_add_i32 m0, s28, 0x18000
	ds_read_b128 v[194:197], v161 offset:49152
	ds_read_b128 v[198:201], v161 offset:50176
	global_load_lds_dwordx4 v144, s[14:15]
	s_add_i32 m0, s28, 0x1a000
	s_add_u32 s98, s98, 0x80
	s_addc_u32 s99, s99, 0
	ds_read_b128 v[202:205], v161 offset:51200
	global_load_lds_dwordx4 v140, s[14:15]
	s_add_i32 m0, s28, 0x1c000
	ds_read_b128 v[206:209], v161 offset:52224
	ds_read_b128 v[210:213], v161 offset:53248
	global_load_lds_dwordx4 v144, s[98:99]
	s_add_i32 m0, s28, 0x1e000
	s_add_u32 s16, s16, 0x80
	s_addc_u32 s17, s17, 0
	ds_read_b128 v[214:217], v161 offset:54272
	ds_read_b128 v[218:221], v161 offset:55296
	global_load_lds_dwordx4 v140, s[98:99]
	s_mov_b32 m0, s39
	ds_read_b128 v[222:225], v161 offset:56320
	global_load_lds_dwordx4 v146, s[16:17]
	s_mov_b32 m0, s44
	s_nop 0
	global_load_lds_dwordx4 v142, s[16:17]
	s_waitcnt vmcnt(8)
	s_waitcnt lgkmcnt(0)
	s_barrier
	v_mfma_f32_16x16x32_bf16 v[62:65], v[152:155], v[194:197], v[62:65]
	v_mfma_f32_16x16x32_bf16 v[62:65], v[162:165], v[198:201], v[62:65]
	v_mfma_f32_16x16x32_bf16 v[58:61], v[166:169], v[194:197], v[58:61]
	v_mfma_f32_16x16x32_bf16 v[58:61], v[170:173], v[198:201], v[58:61]
	v_mfma_f32_16x16x32_bf16 v[46:49], v[152:155], v[202:205], v[46:49]
	v_mfma_f32_16x16x32_bf16 v[46:49], v[162:165], v[206:209], v[46:49]
	v_mfma_f32_16x16x32_bf16 v[42:45], v[166:169], v[202:205], v[42:45]
	v_mfma_f32_16x16x32_bf16 v[42:45], v[170:173], v[206:209], v[42:45]
	v_mfma_f32_16x16x32_bf16 v[30:33], v[152:155], v[210:213], v[30:33]
	v_mfma_f32_16x16x32_bf16 v[30:33], v[162:165], v[214:217], v[30:33]
	v_mfma_f32_16x16x32_bf16 v[26:29], v[166:169], v[210:213], v[26:29]
	v_mfma_f32_16x16x32_bf16 v[26:29], v[170:173], v[214:217], v[26:29]
	v_mfma_f32_16x16x32_bf16 v[14:17], v[152:155], v[218:221], v[14:17]
	v_mfma_f32_16x16x32_bf16 v[14:17], v[162:165], v[222:225], v[14:17]
	v_mfma_f32_16x16x32_bf16 v[10:13], v[166:169], v[218:221], v[10:13]
	v_mfma_f32_16x16x32_bf16 v[10:13], v[170:173], v[222:225], v[10:13]
	v_mfma_f32_16x16x32_bf16 v[54:57], v[174:177], v[194:197], v[54:57]
	v_mfma_f32_16x16x32_bf16 v[54:57], v[182:185], v[198:201], v[54:57]
	v_mfma_f32_16x16x32_bf16 v[50:53], v[186:189], v[194:197], v[50:53]
	v_mfma_f32_16x16x32_bf16 v[50:53], v[190:193], v[198:201], v[50:53]
	v_mfma_f32_16x16x32_bf16 v[38:41], v[174:177], v[202:205], v[38:41]
	v_mfma_f32_16x16x32_bf16 v[38:41], v[182:185], v[206:209], v[38:41]
	v_mfma_f32_16x16x32_bf16 v[34:37], v[186:189], v[202:205], v[34:37]
	v_mfma_f32_16x16x32_bf16 v[34:37], v[190:193], v[206:209], v[34:37]
	v_mfma_f32_16x16x32_bf16 v[22:25], v[174:177], v[210:213], v[22:25]
	v_mfma_f32_16x16x32_bf16 v[22:25], v[182:185], v[214:217], v[22:25]
	v_mfma_f32_16x16x32_bf16 v[18:21], v[186:189], v[210:213], v[18:21]
	v_mfma_f32_16x16x32_bf16 v[18:21], v[190:193], v[214:217], v[18:21]
	v_mfma_f32_16x16x32_bf16 v[6:9], v[174:177], v[218:221], v[6:9]
	v_mfma_f32_16x16x32_bf16 v[6:9], v[182:185], v[222:225], v[6:9]
	v_mfma_f32_16x16x32_bf16 v[2:5], v[186:189], v[218:221], v[2:5]
	v_mfma_f32_16x16x32_bf16 v[2:5], v[190:193], v[222:225], v[2:5]
	s_barrier
	s_add_i32 s35, s35, 2
	s_add_u32 s12, s12, 0x100
	s_addc_u32 s13, s13, 0
	s_add_u32 s0, s0, 0x100
	s_addc_u32 s1, s1, 0
	s_cmp_gt_u32 s35, 61
	s_cbranch_scc0 .LBB0_572
	s_and_b64 vcc, exec, s[10:11]
	s_cbranch_vccz .LBB0_575
	s_barrier

.LBB0_881:
	s_and_b32 s98, s30, 3
	s_and_b32 s99, s28, 7
	s_lshl_b32 s98, s98, 6
	s_lshl_b32 s99, s99, 5
	v_and_b32_e32 v244, 63, v0
	v_and_b32_e32 v244, 7, v244
	v_lshrrev_b32_e32 v245, 6, v0
	v_lshl_add_u32 v244, v245, 3, v244
	v_add_u32_e32 v244, 0x80, v244
	v_cmp_gt_u32_e32 vcc, 0x80, v244
	v_and_b32_e32 v245, 63, v244
	v_add_u32_e32 v245, s98, v245
	v_lshrrev_b32_e32 v246, 6, v244
	v_subrev_u32_e32 v247, 0x80, v244
	v_and_b32_e32 v248, 31, v247
	v_add_u32_e32 v248, s99, v248
	v_lshrrev_b32_e32 v247, 5, v247
	v_cndmask_b32_e32 v245, v248, v245, vcc
	v_cndmask_b32_e32 v246, v247, v246, vcc
	v_lshlrev_b32_e32 v245, 13, v245
	v_lshl_add_u32 v245, v246, 7, v245
	v_add_u32_e32 v244, 0x80, v245
	v_mov_b32_e32 v245, 0
	v_mov_b32_e32 v246, s10
	v_mov_b32_e32 v247, s11
	v_mov_b32_e32 v248, s38
	v_mov_b32_e32 v249, s39
	v_cndmask_b32_e32 v246, v248, v246, vcc
	v_cndmask_b32_e32 v247, v249, v247, vcc
	v_lshl_add_u64 v[242:243], v[246:247], 0, v[244:245]
	v_add_u32_e32 v252, 0x10000, v155
	s_add_u32 s10, s10, 0x100080
	s_addc_u32 s11, s11, 0
	s_add_u32 s0, s38, 0x100
	v_mov_b32_e32 v4, 0
	s_addc_u32 s1, s39, 0
	s_mov_b32 s12, -2
	v_mov_b32_e32 v5, v4
	v_mov_b32_e32 v6, v4
	v_mov_b32_e32 v7, v4
	v_mov_b32_e32 v8, v4
	v_mov_b32_e32 v9, v4
	v_mov_b32_e32 v10, v4
	v_mov_b32_e32 v11, v4
	v_mov_b32_e32 v20, v4
	v_mov_b32_e32 v21, v4
	v_mov_b32_e32 v22, v4
	v_mov_b32_e32 v23, v4
	v_mov_b32_e32 v24, v4
	v_mov_b32_e32 v25, v4
	v_mov_b32_e32 v26, v4
	v_mov_b32_e32 v27, v4
	v_mov_b32_e32 v36, v4
	v_mov_b32_e32 v37, v4
	v_mov_b32_e32 v38, v4
	v_mov_b32_e32 v39, v4
	v_mov_b32_e32 v40, v4
	v_mov_b32_e32 v41, v4
	v_mov_b32_e32 v42, v4
	v_mov_b32_e32 v43, v4
	v_mov_b32_e32 v52, v4
	v_mov_b32_e32 v53, v4
	v_mov_b32_e32 v54, v4
	v_mov_b32_e32 v55, v4
	v_mov_b32_e32 v56, v4
	v_mov_b32_e32 v57, v4
	v_mov_b32_e32 v58, v4
	v_mov_b32_e32 v59, v4
	v_mov_b32_e32 v12, v4
	v_mov_b32_e32 v13, v4
	v_mov_b32_e32 v14, v4
	v_mov_b32_e32 v15, v4
	v_mov_b32_e32 v16, v4
	v_mov_b32_e32 v17, v4
	v_mov_b32_e32 v18, v4
	v_mov_b32_e32 v19, v4
	v_mov_b32_e32 v28, v4
	v_mov_b32_e32 v29, v4
	v_mov_b32_e32 v30, v4
	v_mov_b32_e32 v31, v4
	v_mov_b32_e32 v32, v4
	v_mov_b32_e32 v33, v4
	v_mov_b32_e32 v34, v4
	v_mov_b32_e32 v35, v4
	v_mov_b32_e32 v44, v4
	v_mov_b32_e32 v45, v4
	v_mov_b32_e32 v46, v4
	v_mov_b32_e32 v47, v4
	v_mov_b32_e32 v48, v4
	v_mov_b32_e32 v49, v4
	v_mov_b32_e32 v50, v4
	v_mov_b32_e32 v51, v4
	v_mov_b32_e32 v60, v4
	v_mov_b32_e32 v61, v4
	v_mov_b32_e32 v62, v4
	v_mov_b32_e32 v63, v4
	v_mov_b32_e32 v64, v4
	v_mov_b32_e32 v65, v4
	v_mov_b32_e32 v66, v4
	v_mov_b32_e32 v67, v4
	v_mov_b32_e32 v68, v4
	v_mov_b32_e32 v69, v4
	v_mov_b32_e32 v70, v4
	v_mov_b32_e32 v71, v4
	v_mov_b32_e32 v72, v4
	v_mov_b32_e32 v73, v4
	v_mov_b32_e32 v74, v4
	v_mov_b32_e32 v75, v4
	v_mov_b32_e32 v84, v4
	v_mov_b32_e32 v85, v4
	v_mov_b32_e32 v86, v4
	v_mov_b32_e32 v87, v4
	v_mov_b32_e32 v88, v4
	v_mov_b32_e32 v89, v4
	v_mov_b32_e32 v90, v4
	v_mov_b32_e32 v91, v4
	v_mov_b32_e32 v100, v4
	v_mov_b32_e32 v101, v4
	v_mov_b32_e32 v102, v4
	v_mov_b32_e32 v103, v4
	v_mov_b32_e32 v104, v4
	v_mov_b32_e32 v105, v4
	v_mov_b32_e32 v106, v4
	v_mov_b32_e32 v107, v4
	v_mov_b32_e32 v116, v4
	v_mov_b32_e32 v117, v4
	v_mov_b32_e32 v118, v4
	v_mov_b32_e32 v119, v4
	v_mov_b32_e32 v120, v4
	v_mov_b32_e32 v121, v4
	v_mov_b32_e32 v122, v4
	v_mov_b32_e32 v123, v4
	v_mov_b32_e32 v76, v4
	v_mov_b32_e32 v77, v4
	v_mov_b32_e32 v78, v4
	v_mov_b32_e32 v79, v4
	v_mov_b32_e32 v80, v4
	v_mov_b32_e32 v81, v4
	v_mov_b32_e32 v82, v4
	v_mov_b32_e32 v83, v4
	v_mov_b32_e32 v92, v4
	v_mov_b32_e32 v93, v4
	v_mov_b32_e32 v94, v4
	v_mov_b32_e32 v95, v4
	v_mov_b32_e32 v96, v4
	v_mov_b32_e32 v97, v4
	v_mov_b32_e32 v98, v4
	v_mov_b32_e32 v99, v4
	v_mov_b32_e32 v108, v4
	v_mov_b32_e32 v109, v4
	v_mov_b32_e32 v110, v4
	v_mov_b32_e32 v111, v4
	v_mov_b32_e32 v112, v4
	v_mov_b32_e32 v113, v4
	v_mov_b32_e32 v114, v4
	v_mov_b32_e32 v115, v4
	v_mov_b32_e32 v124, v4
	v_mov_b32_e32 v125, v4
	v_mov_b32_e32 v126, v4
	v_mov_b32_e32 v127, v4
	v_mov_b32_e32 v128, v4
	v_mov_b32_e32 v129, v4
	v_mov_b32_e32 v130, v4
	v_mov_b32_e32 v131, v4
.LBB0_882:
	s_add_u32 s20, s10, 0xfff00080
	s_addc_u32 s21, s11, -1
	s_cmp_eq_u32 s12, 60
	s_cselect_b32 s43, s55, s21
	s_cselect_b32 s42, s54, s20
	s_cselect_b32 s39, s37, s1
	s_cselect_b32 s38, s36, s0
	s_cmp_lt_i32 s12, 57
	s_cselect_b32 s100, 0x100, 0
	s_mov_b32 s101, 0
	v_lshl_add_u64 v[242:243], v[242:243], 0, s[100:101]
	s_add_i32 m0, s29, 0xc000
	ds_read_b128 v[146:149], v252
	ds_read_b128 v[150:153], v252 offset:1024
	global_load_lds_dwordx4 v140, s[10:11]
	s_add_i32 m0, s29, 0xe000
	ds_read_b128 v[158:161], v252 offset:2048
	ds_read_b128 v[162:165], v252 offset:3072
	global_load_lds_dwordx4 v142, s[10:11]
	ds_read_b128 v[166:169], v252 offset:16384
	ds_read_b128 v[170:173], v252 offset:17408
	ds_read_b128 v[174:177], v252 offset:18432
	ds_read_b128 v[186:189], v252 offset:19456
	ds_read_b128 v[190:193], v157
	ds_read_b128 v[194:197], v157 offset:1024
	ds_read_b128 v[198:201], v157 offset:2048
	ds_read_b128 v[202:205], v157 offset:3072
	ds_read_b128 v[206:209], v157 offset:4096
	ds_read_b128 v[210:213], v157 offset:5120
	ds_read_b128 v[214:217], v157 offset:6144
	ds_read_b128 v[218:221], v157 offset:7168
	s_waitcnt vmcnt(8)
	s_mov_b32 m0, 0x21800
	s_mov_b64 exec, 0xff
	s_waitcnt lgkmcnt(0)
	global_load_lds_dword v[242:243], off
	s_mov_b64 exec, -1
	s_barrier
	v_mfma_f32_16x16x32_bf16 v[128:131], v[146:149], v[190:193], v[128:131]
	v_mfma_f32_16x16x32_bf16 v[128:131], v[150:153], v[194:197], v[128:131]
	v_mfma_f32_16x16x32_bf16 v[124:127], v[158:161], v[190:193], v[124:127]
	v_mfma_f32_16x16x32_bf16 v[124:127], v[162:165], v[194:197], v[124:127]
	v_mfma_f32_16x16x32_bf16 v[112:115], v[146:149], v[198:201], v[112:115]
	v_mfma_f32_16x16x32_bf16 v[112:115], v[150:153], v[202:205], v[112:115]
	v_mfma_f32_16x16x32_bf16 v[108:111], v[158:161], v[198:201], v[108:111]
	v_mfma_f32_16x16x32_bf16 v[108:111], v[162:165], v[202:205], v[108:111]
	v_mfma_f32_16x16x32_bf16 v[96:99], v[146:149], v[206:209], v[96:99]
	v_mfma_f32_16x16x32_bf16 v[96:99], v[150:153], v[210:213], v[96:99]
	v_mfma_f32_16x16x32_bf16 v[92:95], v[158:161], v[206:209], v[92:95]
	v_mfma_f32_16x16x32_bf16 v[92:95], v[162:165], v[210:213], v[92:95]
	v_mfma_f32_16x16x32_bf16 v[80:83], v[146:149], v[214:217], v[80:83]
	v_mfma_f32_16x16x32_bf16 v[80:83], v[150:153], v[218:221], v[80:83]
	v_mfma_f32_16x16x32_bf16 v[76:79], v[158:161], v[214:217], v[76:79]
	v_mfma_f32_16x16x32_bf16 v[76:79], v[162:165], v[218:221], v[76:79]
	v_mfma_f32_16x16x32_bf16 v[120:123], v[166:169], v[190:193], v[120:123]
	v_mfma_f32_16x16x32_bf16 v[120:123], v[170:173], v[194:197], v[120:123]
	v_mfma_f32_16x16x32_bf16 v[116:119], v[174:177], v[190:193], v[116:119]
	v_mfma_f32_16x16x32_bf16 v[116:119], v[186:189], v[194:197], v[116:119]
	v_mfma_f32_16x16x32_bf16 v[104:107], v[166:169], v[198:201], v[104:107]
	v_mfma_f32_16x16x32_bf16 v[104:107], v[170:173], v[202:205], v[104:107]
	v_mfma_f32_16x16x32_bf16 v[100:103], v[174:177], v[198:201], v[100:103]
	v_mfma_f32_16x16x32_bf16 v[100:103], v[186:189], v[202:205], v[100:103]
	v_mfma_f32_16x16x32_bf16 v[88:91], v[166:169], v[206:209], v[88:91]
	v_mfma_f32_16x16x32_bf16 v[88:91], v[170:173], v[210:213], v[88:91]
	v_mfma_f32_16x16x32_bf16 v[84:87], v[174:177], v[206:209], v[84:87]
	v_mfma_f32_16x16x32_bf16 v[84:87], v[186:189], v[210:213], v[84:87]
	v_mfma_f32_16x16x32_bf16 v[72:75], v[166:169], v[214:217], v[72:75]
	v_mfma_f32_16x16x32_bf16 v[72:75], v[170:173], v[218:221], v[72:75]
	v_mfma_f32_16x16x32_bf16 v[68:71], v[174:177], v[214:217], v[68:71]
	v_mfma_f32_16x16x32_bf16 v[68:71], v[186:189], v[218:221], v[68:71]
	s_barrier
	s_add_i32 m0, s58, 0x10000
	ds_read_b128 v[190:193], v157 offset:16384
	ds_read_b128 v[194:197], v157 offset:17408
	global_load_lds_dwordx4 v134, s[38:39]
	s_add_i32 m0, s58, 0x12000
	s_add_u32 s98, s38, 0x100000
	s_addc_u32 s99, s39, 0
	ds_read_b128 v[198:201], v157 offset:18432
	global_load_lds_dwordx4 v138, s[38:39]
	s_add_i32 m0, s58, 0x14000
	ds_read_b128 v[202:205], v157 offset:19456
	ds_read_b128 v[206:209], v157 offset:20480
	global_load_lds_dwordx4 v134, s[98:99]
	s_add_i32 m0, s58, 0x16000
	ds_read_b128 v[210:213], v157 offset:21504
	ds_read_b128 v[214:217], v157 offset:22528
	global_load_lds_dwordx4 v138, s[98:99]
	s_mov_b32 m0, s29
	ds_read_b128 v[218:221], v157 offset:23552
	global_load_lds_dwordx4 v132, s[42:43]
	s_mov_b32 m0, s31
	s_nop 0
	global_load_lds_dwordx4 v136, s[42:43]
	s_waitcnt vmcnt(9)
	s_waitcnt lgkmcnt(0)
	s_barrier
	v_mfma_f32_16x16x32_bf16 v[64:67], v[146:149], v[190:193], v[64:67]
	v_mfma_f32_16x16x32_bf16 v[64:67], v[150:153], v[194:197], v[64:67]
	v_mfma_f32_16x16x32_bf16 v[60:63], v[158:161], v[190:193], v[60:63]
	v_mfma_f32_16x16x32_bf16 v[60:63], v[162:165], v[194:197], v[60:63]
	v_mfma_f32_16x16x32_bf16 v[48:51], v[146:149], v[198:201], v[48:51]
	v_mfma_f32_16x16x32_bf16 v[48:51], v[150:153], v[202:205], v[48:51]
	v_mfma_f32_16x16x32_bf16 v[44:47], v[158:161], v[198:201], v[44:47]
	v_mfma_f32_16x16x32_bf16 v[44:47], v[162:165], v[202:205], v[44:47]
	v_mfma_f32_16x16x32_bf16 v[32:35], v[146:149], v[206:209], v[32:35]
	v_mfma_f32_16x16x32_bf16 v[32:35], v[150:153], v[210:213], v[32:35]
	v_mfma_f32_16x16x32_bf16 v[28:31], v[158:161], v[206:209], v[28:31]
	v_mfma_f32_16x16x32_bf16 v[28:31], v[162:165], v[210:213], v[28:31]
	v_mfma_f32_16x16x32_bf16 v[16:19], v[146:149], v[214:217], v[16:19]
	v_mfma_f32_16x16x32_bf16 v[16:19], v[150:153], v[218:221], v[16:19]
	v_mfma_f32_16x16x32_bf16 v[12:15], v[158:161], v[214:217], v[12:15]
	v_mfma_f32_16x16x32_bf16 v[12:15], v[162:165], v[218:221], v[12:15]
	v_mfma_f32_16x16x32_bf16 v[56:59], v[166:169], v[190:193], v[56:59]
	v_mfma_f32_16x16x32_bf16 v[56:59], v[170:173], v[194:197], v[56:59]
	v_mfma_f32_16x16x32_bf16 v[52:55], v[174:177], v[190:193], v[52:55]
	v_mfma_f32_16x16x32_bf16 v[52:55], v[186:189], v[194:197], v[52:55]
	v_mfma_f32_16x16x32_bf16 v[40:43], v[166:169], v[198:201], v[40:43]
	v_mfma_f32_16x16x32_bf16 v[40:43], v[170:173], v[202:205], v[40:43]
	v_mfma_f32_16x16x32_bf16 v[36:39], v[174:177], v[198:201], v[36:39]
	v_mfma_f32_16x16x32_bf16 v[36:39], v[186:189], v[202:205], v[36:39]
	v_mfma_f32_16x16x32_bf16 v[24:27], v[166:169], v[206:209], v[24:27]
	v_mfma_f32_16x16x32_bf16 v[24:27], v[170:173], v[210:213], v[24:27]
	v_mfma_f32_16x16x32_bf16 v[20:23], v[174:177], v[206:209], v[20:23]
	v_mfma_f32_16x16x32_bf16 v[20:23], v[186:189], v[210:213], v[20:23]
	v_mfma_f32_16x16x32_bf16 v[8:11], v[166:169], v[214:217], v[8:11]
	v_mfma_f32_16x16x32_bf16 v[8:11], v[170:173], v[218:221], v[8:11]
	v_mfma_f32_16x16x32_bf16 v[4:7], v[174:177], v[214:217], v[4:7]
	v_mfma_f32_16x16x32_bf16 v[4:7], v[186:189], v[218:221], v[4:7]
	s_barrier
	s_add_u32 s100, s42, 0x100000
	s_addc_u32 s101, s43, 0
	s_mov_b32 m0, s59
	ds_read_b128 v[146:149], v252 offset:32768
	ds_read_b128 v[150:153], v252 offset:33792
	global_load_lds_dwordx4 v132, s[100:101]
	s_mov_b32 m0, s94
	ds_read_b128 v[158:161], v252 offset:34816
	ds_read_b128 v[162:165], v252 offset:35840
	global_load_lds_dwordx4 v136, s[100:101]
	ds_read_b128 v[166:169], v252 offset:49152
	ds_read_b128 v[170:173], v252 offset:50176
	ds_read_b128 v[174:177], v252 offset:51200
	ds_read_b128 v[186:189], v252 offset:52224
	ds_read_b128 v[190:193], v157 offset:32768
	ds_read_b128 v[194:197], v157 offset:33792
	ds_read_b128 v[198:201], v157 offset:34816
	ds_read_b128 v[202:205], v157 offset:35840
	ds_read_b128 v[206:209], v157 offset:36864
	ds_read_b128 v[210:213], v157 offset:37888
	ds_read_b128 v[214:217], v157 offset:38912
	ds_read_b128 v[218:221], v157 offset:39936
	s_waitcnt vmcnt(9)
	s_waitcnt lgkmcnt(0)
	s_barrier
	v_mfma_f32_16x16x32_bf16 v[128:131], v[146:149], v[190:193], v[128:131]
	v_mfma_f32_16x16x32_bf16 v[128:131], v[150:153], v[194:197], v[128:131]
	v_mfma_f32_16x16x32_bf16 v[124:127], v[158:161], v[190:193], v[124:127]
	v_mfma_f32_16x16x32_bf16 v[124:127], v[162:165], v[194:197], v[124:127]
	v_mfma_f32_16x16x32_bf16 v[112:115], v[146:149], v[198:201], v[112:115]
	v_mfma_f32_16x16x32_bf16 v[112:115], v[150:153], v[202:205], v[112:115]
	v_mfma_f32_16x16x32_bf16 v[108:111], v[158:161], v[198:201], v[108:111]
	v_mfma_f32_16x16x32_bf16 v[108:111], v[162:165], v[202:205], v[108:111]
	v_mfma_f32_16x16x32_bf16 v[96:99], v[146:149], v[206:209], v[96:99]
	v_mfma_f32_16x16x32_bf16 v[96:99], v[150:153], v[210:213], v[96:99]
	v_mfma_f32_16x16x32_bf16 v[92:95], v[158:161], v[206:209], v[92:95]
	v_mfma_f32_16x16x32_bf16 v[92:95], v[162:165], v[210:213], v[92:95]
	v_mfma_f32_16x16x32_bf16 v[80:83], v[146:149], v[214:217], v[80:83]
	v_mfma_f32_16x16x32_bf16 v[80:83], v[150:153], v[218:221], v[80:83]
	v_mfma_f32_16x16x32_bf16 v[76:79], v[158:161], v[214:217], v[76:79]
	v_mfma_f32_16x16x32_bf16 v[76:79], v[162:165], v[218:221], v[76:79]
	v_mfma_f32_16x16x32_bf16 v[120:123], v[166:169], v[190:193], v[120:123]
	v_mfma_f32_16x16x32_bf16 v[120:123], v[170:173], v[194:197], v[120:123]
	v_mfma_f32_16x16x32_bf16 v[116:119], v[174:177], v[190:193], v[116:119]
	v_mfma_f32_16x16x32_bf16 v[116:119], v[186:189], v[194:197], v[116:119]
	v_mfma_f32_16x16x32_bf16 v[104:107], v[166:169], v[198:201], v[104:107]
	v_mfma_f32_16x16x32_bf16 v[104:107], v[170:173], v[202:205], v[104:107]
	v_mfma_f32_16x16x32_bf16 v[100:103], v[174:177], v[198:201], v[100:103]
	v_mfma_f32_16x16x32_bf16 v[100:103], v[186:189], v[202:205], v[100:103]
	v_mfma_f32_16x16x32_bf16 v[88:91], v[166:169], v[206:209], v[88:91]
	v_mfma_f32_16x16x32_bf16 v[88:91], v[170:173], v[210:213], v[88:91]
	v_mfma_f32_16x16x32_bf16 v[84:87], v[174:177], v[206:209], v[84:87]
	v_mfma_f32_16x16x32_bf16 v[84:87], v[186:189], v[210:213], v[84:87]
	v_mfma_f32_16x16x32_bf16 v[72:75], v[166:169], v[214:217], v[72:75]
	v_mfma_f32_16x16x32_bf16 v[72:75], v[170:173], v[218:221], v[72:75]
	v_mfma_f32_16x16x32_bf16 v[68:71], v[174:177], v[214:217], v[68:71]
	v_mfma_f32_16x16x32_bf16 v[68:71], v[186:189], v[218:221], v[68:71]
	s_barrier
	s_add_u32 s38, s38, 0x80
	s_addc_u32 s39, s39, 0
	s_add_i32 m0, s58, 0x18000
	ds_read_b128 v[190:193], v157 offset:49152
	ds_read_b128 v[194:197], v157 offset:50176
	global_load_lds_dwordx4 v134, s[38:39]
	s_add_i32 m0, s58, 0x1a000
	s_add_u32 s98, s98, 0x80
	s_addc_u32 s99, s99, 0
	ds_read_b128 v[198:201], v157 offset:51200
	global_load_lds_dwordx4 v138, s[38:39]
	s_add_i32 m0, s58, 0x1c000
	ds_read_b128 v[202:205], v157 offset:52224
	ds_read_b128 v[206:209], v157 offset:53248
	global_load_lds_dwordx4 v134, s[98:99]
	s_add_i32 m0, s58, 0x1e000
	s_add_u32 s42, s42, 0x80
	s_addc_u32 s43, s43, 0
	ds_read_b128 v[210:213], v157 offset:54272
	ds_read_b128 v[214:217], v157 offset:55296
	global_load_lds_dwordx4 v138, s[98:99]
	s_mov_b32 m0, s14
	ds_read_b128 v[218:221], v157 offset:56320
	global_load_lds_dwordx4 v132, s[42:43]
	s_mov_b32 m0, s15
	s_nop 0
	global_load_lds_dwordx4 v136, s[42:43]
	s_waitcnt vmcnt(8)
	s_waitcnt lgkmcnt(0)
	s_barrier
	v_mfma_f32_16x16x32_bf16 v[64:67], v[146:149], v[190:193], v[64:67]
	v_mfma_f32_16x16x32_bf16 v[64:67], v[150:153], v[194:197], v[64:67]
	v_mfma_f32_16x16x32_bf16 v[60:63], v[158:161], v[190:193], v[60:63]
	v_mfma_f32_16x16x32_bf16 v[60:63], v[162:165], v[194:197], v[60:63]
	v_mfma_f32_16x16x32_bf16 v[48:51], v[146:149], v[198:201], v[48:51]
	v_mfma_f32_16x16x32_bf16 v[48:51], v[150:153], v[202:205], v[48:51]
	v_mfma_f32_16x16x32_bf16 v[44:47], v[158:161], v[198:201], v[44:47]
	v_mfma_f32_16x16x32_bf16 v[44:47], v[162:165], v[202:205], v[44:47]
	v_mfma_f32_16x16x32_bf16 v[32:35], v[146:149], v[206:209], v[32:35]
	v_mfma_f32_16x16x32_bf16 v[32:35], v[150:153], v[210:213], v[32:35]
	v_mfma_f32_16x16x32_bf16 v[28:31], v[158:161], v[206:209], v[28:31]
	v_mfma_f32_16x16x32_bf16 v[28:31], v[162:165], v[210:213], v[28:31]
	v_mfma_f32_16x16x32_bf16 v[16:19], v[146:149], v[214:217], v[16:19]
	v_mfma_f32_16x16x32_bf16 v[16:19], v[150:153], v[218:221], v[16:19]
	v_mfma_f32_16x16x32_bf16 v[12:15], v[158:161], v[214:217], v[12:15]
	v_mfma_f32_16x16x32_bf16 v[12:15], v[162:165], v[218:221], v[12:15]
	v_mfma_f32_16x16x32_bf16 v[56:59], v[166:169], v[190:193], v[56:59]
	v_mfma_f32_16x16x32_bf16 v[56:59], v[170:173], v[194:197], v[56:59]
	v_mfma_f32_16x16x32_bf16 v[52:55], v[174:177], v[190:193], v[52:55]
	v_mfma_f32_16x16x32_bf16 v[52:55], v[186:189], v[194:197], v[52:55]
	v_mfma_f32_16x16x32_bf16 v[40:43], v[166:169], v[198:201], v[40:43]
	v_mfma_f32_16x16x32_bf16 v[40:43], v[170:173], v[202:205], v[40:43]
	v_mfma_f32_16x16x32_bf16 v[36:39], v[174:177], v[198:201], v[36:39]
	v_mfma_f32_16x16x32_bf16 v[36:39], v[186:189], v[202:205], v[36:39]
	v_mfma_f32_16x16x32_bf16 v[24:27], v[166:169], v[206:209], v[24:27]
	v_mfma_f32_16x16x32_bf16 v[24:27], v[170:173], v[210:213], v[24:27]
	v_mfma_f32_16x16x32_bf16 v[20:23], v[174:177], v[206:209], v[20:23]
	v_mfma_f32_16x16x32_bf16 v[20:23], v[186:189], v[210:213], v[20:23]
	v_mfma_f32_16x16x32_bf16 v[8:11], v[166:169], v[214:217], v[8:11]
	v_mfma_f32_16x16x32_bf16 v[8:11], v[170:173], v[218:221], v[8:11]
	v_mfma_f32_16x16x32_bf16 v[4:7], v[174:177], v[214:217], v[4:7]
	v_mfma_f32_16x16x32_bf16 v[4:7], v[186:189], v[218:221], v[4:7]
	s_barrier
	s_add_i32 s12, s12, 2
	s_add_u32 s10, s10, 0x100
	s_addc_u32 s11, s11, 0
	s_add_u32 s0, s0, 0x100
	s_addc_u32 s1, s1, 0
	s_cmp_gt_u32 s12, 61
	s_cbranch_scc0 .LBB0_882
	s_and_b64 vcc, exec, s[48:49]
	s_cbranch_vccz .LBB0_885
	s_barrier

.LBB0_1225:
	s_and_b32 s98, s59, 3
	s_and_b32 s99, s58, 7
	s_lshl_b32 s98, s98, 6
	s_lshl_b32 s99, s99, 5
	v_and_b32_e32 v244, 63, v0
	v_and_b32_e32 v244, 7, v244
	v_lshrrev_b32_e32 v245, 6, v0
	v_lshl_add_u32 v244, v245, 3, v244
	v_add_u32_e32 v244, 0x80, v244
	v_cmp_gt_u32_e32 vcc, 0x80, v244
	v_and_b32_e32 v245, 63, v244
	v_add_u32_e32 v245, s98, v245
	v_lshrrev_b32_e32 v246, 6, v244
	v_subrev_u32_e32 v247, 0x80, v244
	v_and_b32_e32 v248, 31, v247
	v_add_u32_e32 v248, s99, v248
	v_lshrrev_b32_e32 v247, 5, v247
	v_cndmask_b32_e32 v245, v248, v245, vcc
	v_cndmask_b32_e32 v246, v247, v246, vcc
	v_lshlrev_b32_e32 v245, 13, v245
	v_lshl_add_u32 v245, v246, 7, v245
	v_add_u32_e32 v244, 0x80, v245
	v_mov_b32_e32 v245, 0
	v_mov_b32_e32 v246, s10
	v_mov_b32_e32 v247, s11
	v_mov_b32_e32 v248, s28
	v_mov_b32_e32 v249, s29
	v_cndmask_b32_e32 v246, v248, v246, vcc
	v_cndmask_b32_e32 v247, v249, v247, vcc
	v_lshl_add_u64 v[242:243], v[246:247], 0, v[244:245]
	v_add_u32_e32 v252, 0x10000, v151
	s_add_u32 s10, s10, 0x100080
	s_addc_u32 s11, s11, 0
	s_add_u32 s0, s28, 0x100
	v_mov_b32_e32 v4, 0
	s_addc_u32 s1, s29, 0
	s_mov_b32 s20, -2
	v_mov_b32_e32 v5, v4
	v_mov_b32_e32 v6, v4
	v_mov_b32_e32 v7, v4
	v_mov_b32_e32 v8, v4
	v_mov_b32_e32 v9, v4
	v_mov_b32_e32 v10, v4
	v_mov_b32_e32 v11, v4
	v_mov_b32_e32 v20, v4
	v_mov_b32_e32 v21, v4
	v_mov_b32_e32 v22, v4
	v_mov_b32_e32 v23, v4
	v_mov_b32_e32 v24, v4
	v_mov_b32_e32 v25, v4
	v_mov_b32_e32 v26, v4
	v_mov_b32_e32 v27, v4
	v_mov_b32_e32 v36, v4
	v_mov_b32_e32 v37, v4
	v_mov_b32_e32 v38, v4
	v_mov_b32_e32 v39, v4
	v_mov_b32_e32 v40, v4
	v_mov_b32_e32 v41, v4
	v_mov_b32_e32 v42, v4
	v_mov_b32_e32 v43, v4
	v_mov_b32_e32 v52, v4
	v_mov_b32_e32 v53, v4
	v_mov_b32_e32 v54, v4
	v_mov_b32_e32 v55, v4
	v_mov_b32_e32 v56, v4
	v_mov_b32_e32 v57, v4
	v_mov_b32_e32 v58, v4
	v_mov_b32_e32 v59, v4
	v_mov_b32_e32 v12, v4
	v_mov_b32_e32 v13, v4
	v_mov_b32_e32 v14, v4
	v_mov_b32_e32 v15, v4
	v_mov_b32_e32 v16, v4
	v_mov_b32_e32 v17, v4
	v_mov_b32_e32 v18, v4
	v_mov_b32_e32 v19, v4
	v_mov_b32_e32 v28, v4
	v_mov_b32_e32 v29, v4
	v_mov_b32_e32 v30, v4
	v_mov_b32_e32 v31, v4
	v_mov_b32_e32 v32, v4
	v_mov_b32_e32 v33, v4
	v_mov_b32_e32 v34, v4
	v_mov_b32_e32 v35, v4
	v_mov_b32_e32 v44, v4
	v_mov_b32_e32 v45, v4
	v_mov_b32_e32 v46, v4
	v_mov_b32_e32 v47, v4
	v_mov_b32_e32 v48, v4
	v_mov_b32_e32 v49, v4
	v_mov_b32_e32 v50, v4
	v_mov_b32_e32 v51, v4
	v_mov_b32_e32 v60, v4
	v_mov_b32_e32 v61, v4
	v_mov_b32_e32 v62, v4
	v_mov_b32_e32 v63, v4
	v_mov_b32_e32 v64, v4
	v_mov_b32_e32 v65, v4
	v_mov_b32_e32 v66, v4
	v_mov_b32_e32 v67, v4
	v_mov_b32_e32 v68, v4
	v_mov_b32_e32 v69, v4
	v_mov_b32_e32 v70, v4
	v_mov_b32_e32 v71, v4
	v_mov_b32_e32 v72, v4
	v_mov_b32_e32 v73, v4
	v_mov_b32_e32 v74, v4
	v_mov_b32_e32 v75, v4
	v_mov_b32_e32 v84, v4
	v_mov_b32_e32 v85, v4
	v_mov_b32_e32 v86, v4
	v_mov_b32_e32 v87, v4
	v_mov_b32_e32 v88, v4
	v_mov_b32_e32 v89, v4
	v_mov_b32_e32 v90, v4
	v_mov_b32_e32 v91, v4
	v_mov_b32_e32 v100, v4
	v_mov_b32_e32 v101, v4
	v_mov_b32_e32 v102, v4
	v_mov_b32_e32 v103, v4
	v_mov_b32_e32 v104, v4
	v_mov_b32_e32 v105, v4
	v_mov_b32_e32 v106, v4
	v_mov_b32_e32 v107, v4
	v_mov_b32_e32 v116, v4
	v_mov_b32_e32 v117, v4
	v_mov_b32_e32 v118, v4
	v_mov_b32_e32 v119, v4
	v_mov_b32_e32 v120, v4
	v_mov_b32_e32 v121, v4
	v_mov_b32_e32 v122, v4
	v_mov_b32_e32 v123, v4
	v_mov_b32_e32 v76, v4
	v_mov_b32_e32 v77, v4
	v_mov_b32_e32 v78, v4
	v_mov_b32_e32 v79, v4
	v_mov_b32_e32 v80, v4
	v_mov_b32_e32 v81, v4
	v_mov_b32_e32 v82, v4
	v_mov_b32_e32 v83, v4
	v_mov_b32_e32 v92, v4
	v_mov_b32_e32 v93, v4
	v_mov_b32_e32 v94, v4
	v_mov_b32_e32 v95, v4
	v_mov_b32_e32 v96, v4
	v_mov_b32_e32 v97, v4
	v_mov_b32_e32 v98, v4
	v_mov_b32_e32 v99, v4
	v_mov_b32_e32 v108, v4
	v_mov_b32_e32 v109, v4
	v_mov_b32_e32 v110, v4
	v_mov_b32_e32 v111, v4
	v_mov_b32_e32 v112, v4
	v_mov_b32_e32 v113, v4
	v_mov_b32_e32 v114, v4
	v_mov_b32_e32 v115, v4
	v_mov_b32_e32 v124, v4
	v_mov_b32_e32 v125, v4
	v_mov_b32_e32 v126, v4
	v_mov_b32_e32 v127, v4
	v_mov_b32_e32 v128, v4
	v_mov_b32_e32 v129, v4
	v_mov_b32_e32 v130, v4
	v_mov_b32_e32 v131, v4
.LBB0_1226:
	s_add_u32 s21, s10, 0xfff00080
	s_addc_u32 s22, s11, -1
	s_cmp_eq_u32 s20, 60
	s_cselect_b32 s31, s53, s22
	s_cselect_b32 s30, s52, s21
	s_cselect_b32 s29, s55, s1
	s_cselect_b32 s28, s54, s0
	s_cmp_lt_i32 s20, 57
	s_cselect_b32 s100, 0x100, 0
	s_mov_b32 s101, 0
	v_lshl_add_u64 v[242:243], v[242:243], 0, s[100:101]
	s_add_i32 m0, s8, 0xc000
	ds_read_b128 v[144:147], v252
	ds_read_b128 v[154:157], v252 offset:1024
	global_load_lds_dwordx4 v140, s[10:11]
	s_add_i32 m0, s8, 0xe000
	ds_read_b128 v[158:161], v252 offset:2048
	ds_read_b128 v[162:165], v252 offset:3072
	global_load_lds_dwordx4 v142, s[10:11]
	ds_read_b128 v[166:169], v252 offset:16384
	ds_read_b128 v[170:173], v252 offset:17408
	ds_read_b128 v[174:177], v252 offset:18432
	ds_read_b128 v[186:189], v252 offset:19456
	ds_read_b128 v[190:193], v153
	ds_read_b128 v[194:197], v153 offset:1024
	ds_read_b128 v[198:201], v153 offset:2048
	ds_read_b128 v[202:205], v153 offset:3072
	ds_read_b128 v[206:209], v153 offset:4096
	ds_read_b128 v[210:213], v153 offset:5120
	ds_read_b128 v[214:217], v153 offset:6144
	ds_read_b128 v[218:221], v153 offset:7168
	s_waitcnt vmcnt(8)
	s_mov_b32 m0, 0x21800
	s_mov_b64 exec, 0xff
	s_waitcnt lgkmcnt(0)
	global_load_lds_dword v[242:243], off
	s_mov_b64 exec, -1
	s_barrier
	v_mfma_f32_16x16x32_bf16 v[128:131], v[144:147], v[190:193], v[128:131]
	v_mfma_f32_16x16x32_bf16 v[128:131], v[154:157], v[194:197], v[128:131]
	v_mfma_f32_16x16x32_bf16 v[124:127], v[158:161], v[190:193], v[124:127]
	v_mfma_f32_16x16x32_bf16 v[124:127], v[162:165], v[194:197], v[124:127]
	v_mfma_f32_16x16x32_bf16 v[112:115], v[144:147], v[198:201], v[112:115]
	v_mfma_f32_16x16x32_bf16 v[112:115], v[154:157], v[202:205], v[112:115]
	v_mfma_f32_16x16x32_bf16 v[108:111], v[158:161], v[198:201], v[108:111]
	v_mfma_f32_16x16x32_bf16 v[108:111], v[162:165], v[202:205], v[108:111]
	v_mfma_f32_16x16x32_bf16 v[96:99], v[144:147], v[206:209], v[96:99]
	v_mfma_f32_16x16x32_bf16 v[96:99], v[154:157], v[210:213], v[96:99]
	v_mfma_f32_16x16x32_bf16 v[92:95], v[158:161], v[206:209], v[92:95]
	v_mfma_f32_16x16x32_bf16 v[92:95], v[162:165], v[210:213], v[92:95]
	v_mfma_f32_16x16x32_bf16 v[80:83], v[144:147], v[214:217], v[80:83]
	v_mfma_f32_16x16x32_bf16 v[80:83], v[154:157], v[218:221], v[80:83]
	v_mfma_f32_16x16x32_bf16 v[76:79], v[158:161], v[214:217], v[76:79]
	v_mfma_f32_16x16x32_bf16 v[76:79], v[162:165], v[218:221], v[76:79]
	v_mfma_f32_16x16x32_bf16 v[120:123], v[166:169], v[190:193], v[120:123]
	v_mfma_f32_16x16x32_bf16 v[120:123], v[170:173], v[194:197], v[120:123]
	v_mfma_f32_16x16x32_bf16 v[116:119], v[174:177], v[190:193], v[116:119]
	v_mfma_f32_16x16x32_bf16 v[116:119], v[186:189], v[194:197], v[116:119]
	v_mfma_f32_16x16x32_bf16 v[104:107], v[166:169], v[198:201], v[104:107]
	v_mfma_f32_16x16x32_bf16 v[104:107], v[170:173], v[202:205], v[104:107]
	v_mfma_f32_16x16x32_bf16 v[100:103], v[174:177], v[198:201], v[100:103]
	v_mfma_f32_16x16x32_bf16 v[100:103], v[186:189], v[202:205], v[100:103]
	v_mfma_f32_16x16x32_bf16 v[88:91], v[166:169], v[206:209], v[88:91]
	v_mfma_f32_16x16x32_bf16 v[88:91], v[170:173], v[210:213], v[88:91]
	v_mfma_f32_16x16x32_bf16 v[84:87], v[174:177], v[206:209], v[84:87]
	v_mfma_f32_16x16x32_bf16 v[84:87], v[186:189], v[210:213], v[84:87]
	v_mfma_f32_16x16x32_bf16 v[72:75], v[166:169], v[214:217], v[72:75]
	v_mfma_f32_16x16x32_bf16 v[72:75], v[170:173], v[218:221], v[72:75]
	v_mfma_f32_16x16x32_bf16 v[68:71], v[174:177], v[214:217], v[68:71]
	v_mfma_f32_16x16x32_bf16 v[68:71], v[186:189], v[218:221], v[68:71]
	s_barrier
	s_add_i32 m0, s38, 0x10000
	ds_read_b128 v[190:193], v153 offset:16384
	ds_read_b128 v[194:197], v153 offset:17408
	global_load_lds_dwordx4 v136, s[28:29]
	s_add_i32 m0, s38, 0x12000
	s_add_u32 s98, s28, 0x100000
	s_addc_u32 s99, s29, 0
	ds_read_b128 v[198:201], v153 offset:18432
	global_load_lds_dwordx4 v132, s[28:29]
	s_add_i32 m0, s38, 0x14000
	ds_read_b128 v[202:205], v153 offset:19456
	ds_read_b128 v[206:209], v153 offset:20480
	global_load_lds_dwordx4 v136, s[98:99]
	s_add_i32 m0, s38, 0x16000
	ds_read_b128 v[210:213], v153 offset:21504
	ds_read_b128 v[214:217], v153 offset:22528
	global_load_lds_dwordx4 v132, s[98:99]
	s_mov_b32 m0, s8
	ds_read_b128 v[218:221], v153 offset:23552
	global_load_lds_dwordx4 v138, s[30:31]
	s_mov_b32 m0, s9
	s_nop 0
	global_load_lds_dwordx4 v134, s[30:31]
	s_waitcnt vmcnt(9)
	s_waitcnt lgkmcnt(0)
	s_barrier
	v_mfma_f32_16x16x32_bf16 v[64:67], v[144:147], v[190:193], v[64:67]
	v_mfma_f32_16x16x32_bf16 v[64:67], v[154:157], v[194:197], v[64:67]
	v_mfma_f32_16x16x32_bf16 v[60:63], v[158:161], v[190:193], v[60:63]
	v_mfma_f32_16x16x32_bf16 v[60:63], v[162:165], v[194:197], v[60:63]
	v_mfma_f32_16x16x32_bf16 v[48:51], v[144:147], v[198:201], v[48:51]
	v_mfma_f32_16x16x32_bf16 v[48:51], v[154:157], v[202:205], v[48:51]
	v_mfma_f32_16x16x32_bf16 v[44:47], v[158:161], v[198:201], v[44:47]
	v_mfma_f32_16x16x32_bf16 v[44:47], v[162:165], v[202:205], v[44:47]
	v_mfma_f32_16x16x32_bf16 v[32:35], v[144:147], v[206:209], v[32:35]
	v_mfma_f32_16x16x32_bf16 v[32:35], v[154:157], v[210:213], v[32:35]
	v_mfma_f32_16x16x32_bf16 v[28:31], v[158:161], v[206:209], v[28:31]
	v_mfma_f32_16x16x32_bf16 v[28:31], v[162:165], v[210:213], v[28:31]
	v_mfma_f32_16x16x32_bf16 v[16:19], v[144:147], v[214:217], v[16:19]
	v_mfma_f32_16x16x32_bf16 v[16:19], v[154:157], v[218:221], v[16:19]
	v_mfma_f32_16x16x32_bf16 v[12:15], v[158:161], v[214:217], v[12:15]
	v_mfma_f32_16x16x32_bf16 v[12:15], v[162:165], v[218:221], v[12:15]
	v_mfma_f32_16x16x32_bf16 v[56:59], v[166:169], v[190:193], v[56:59]
	v_mfma_f32_16x16x32_bf16 v[56:59], v[170:173], v[194:197], v[56:59]
	v_mfma_f32_16x16x32_bf16 v[52:55], v[174:177], v[190:193], v[52:55]
	v_mfma_f32_16x16x32_bf16 v[52:55], v[186:189], v[194:197], v[52:55]
	v_mfma_f32_16x16x32_bf16 v[40:43], v[166:169], v[198:201], v[40:43]
	v_mfma_f32_16x16x32_bf16 v[40:43], v[170:173], v[202:205], v[40:43]
	v_mfma_f32_16x16x32_bf16 v[36:39], v[174:177], v[198:201], v[36:39]
	v_mfma_f32_16x16x32_bf16 v[36:39], v[186:189], v[202:205], v[36:39]
	v_mfma_f32_16x16x32_bf16 v[24:27], v[166:169], v[206:209], v[24:27]
	v_mfma_f32_16x16x32_bf16 v[24:27], v[170:173], v[210:213], v[24:27]
	v_mfma_f32_16x16x32_bf16 v[20:23], v[174:177], v[206:209], v[20:23]
	v_mfma_f32_16x16x32_bf16 v[20:23], v[186:189], v[210:213], v[20:23]
	v_mfma_f32_16x16x32_bf16 v[8:11], v[166:169], v[214:217], v[8:11]
	v_mfma_f32_16x16x32_bf16 v[8:11], v[170:173], v[218:221], v[8:11]
	v_mfma_f32_16x16x32_bf16 v[4:7], v[174:177], v[214:217], v[4:7]
	v_mfma_f32_16x16x32_bf16 v[4:7], v[186:189], v[218:221], v[4:7]
	s_barrier
	s_add_u32 s100, s30, 0x100000
	s_addc_u32 s101, s31, 0
	s_mov_b32 m0, s16
	ds_read_b128 v[144:147], v252 offset:32768
	ds_read_b128 v[154:157], v252 offset:33792
	global_load_lds_dwordx4 v138, s[100:101]
	s_mov_b32 m0, s17
	ds_read_b128 v[158:161], v252 offset:34816
	ds_read_b128 v[162:165], v252 offset:35840
	global_load_lds_dwordx4 v134, s[100:101]
	ds_read_b128 v[166:169], v252 offset:49152
	ds_read_b128 v[170:173], v252 offset:50176
	ds_read_b128 v[174:177], v252 offset:51200
	ds_read_b128 v[186:189], v252 offset:52224
	ds_read_b128 v[190:193], v153 offset:32768
	ds_read_b128 v[194:197], v153 offset:33792
	ds_read_b128 v[198:201], v153 offset:34816
	ds_read_b128 v[202:205], v153 offset:35840
	ds_read_b128 v[206:209], v153 offset:36864
	ds_read_b128 v[210:213], v153 offset:37888
	ds_read_b128 v[214:217], v153 offset:38912
	ds_read_b128 v[218:221], v153 offset:39936
	s_waitcnt vmcnt(9)
	s_waitcnt lgkmcnt(0)
	s_barrier
	v_mfma_f32_16x16x32_bf16 v[128:131], v[144:147], v[190:193], v[128:131]
	v_mfma_f32_16x16x32_bf16 v[128:131], v[154:157], v[194:197], v[128:131]
	v_mfma_f32_16x16x32_bf16 v[124:127], v[158:161], v[190:193], v[124:127]
	v_mfma_f32_16x16x32_bf16 v[124:127], v[162:165], v[194:197], v[124:127]
	v_mfma_f32_16x16x32_bf16 v[112:115], v[144:147], v[198:201], v[112:115]
	v_mfma_f32_16x16x32_bf16 v[112:115], v[154:157], v[202:205], v[112:115]
	v_mfma_f32_16x16x32_bf16 v[108:111], v[158:161], v[198:201], v[108:111]
	v_mfma_f32_16x16x32_bf16 v[108:111], v[162:165], v[202:205], v[108:111]
	v_mfma_f32_16x16x32_bf16 v[96:99], v[144:147], v[206:209], v[96:99]
	v_mfma_f32_16x16x32_bf16 v[96:99], v[154:157], v[210:213], v[96:99]
	v_mfma_f32_16x16x32_bf16 v[92:95], v[158:161], v[206:209], v[92:95]
	v_mfma_f32_16x16x32_bf16 v[92:95], v[162:165], v[210:213], v[92:95]
	v_mfma_f32_16x16x32_bf16 v[80:83], v[144:147], v[214:217], v[80:83]
	v_mfma_f32_16x16x32_bf16 v[80:83], v[154:157], v[218:221], v[80:83]
	v_mfma_f32_16x16x32_bf16 v[76:79], v[158:161], v[214:217], v[76:79]
	v_mfma_f32_16x16x32_bf16 v[76:79], v[162:165], v[218:221], v[76:79]
	v_mfma_f32_16x16x32_bf16 v[120:123], v[166:169], v[190:193], v[120:123]
	v_mfma_f32_16x16x32_bf16 v[120:123], v[170:173], v[194:197], v[120:123]
	v_mfma_f32_16x16x32_bf16 v[116:119], v[174:177], v[190:193], v[116:119]
	v_mfma_f32_16x16x32_bf16 v[116:119], v[186:189], v[194:197], v[116:119]
	v_mfma_f32_16x16x32_bf16 v[104:107], v[166:169], v[198:201], v[104:107]
	v_mfma_f32_16x16x32_bf16 v[104:107], v[170:173], v[202:205], v[104:107]
	v_mfma_f32_16x16x32_bf16 v[100:103], v[174:177], v[198:201], v[100:103]
	v_mfma_f32_16x16x32_bf16 v[100:103], v[186:189], v[202:205], v[100:103]
	v_mfma_f32_16x16x32_bf16 v[88:91], v[166:169], v[206:209], v[88:91]
	v_mfma_f32_16x16x32_bf16 v[88:91], v[170:173], v[210:213], v[88:91]
	v_mfma_f32_16x16x32_bf16 v[84:87], v[174:177], v[206:209], v[84:87]
	v_mfma_f32_16x16x32_bf16 v[84:87], v[186:189], v[210:213], v[84:87]
	v_mfma_f32_16x16x32_bf16 v[72:75], v[166:169], v[214:217], v[72:75]
	v_mfma_f32_16x16x32_bf16 v[72:75], v[170:173], v[218:221], v[72:75]
	v_mfma_f32_16x16x32_bf16 v[68:71], v[174:177], v[214:217], v[68:71]
	v_mfma_f32_16x16x32_bf16 v[68:71], v[186:189], v[218:221], v[68:71]
	s_barrier
	s_add_u32 s28, s28, 0x80
	s_addc_u32 s29, s29, 0
	s_add_i32 m0, s38, 0x18000
	ds_read_b128 v[190:193], v153 offset:49152
	ds_read_b128 v[194:197], v153 offset:50176
	global_load_lds_dwordx4 v136, s[28:29]
	s_add_i32 m0, s38, 0x1a000
	s_add_u32 s98, s98, 0x80
	s_addc_u32 s99, s99, 0
	ds_read_b128 v[198:201], v153 offset:51200
	global_load_lds_dwordx4 v132, s[28:29]
	s_add_i32 m0, s38, 0x1c000
	ds_read_b128 v[202:205], v153 offset:52224
	ds_read_b128 v[206:209], v153 offset:53248
	global_load_lds_dwordx4 v136, s[98:99]
	s_add_i32 m0, s38, 0x1e000
	s_add_u32 s30, s30, 0x80
	s_addc_u32 s31, s31, 0
	ds_read_b128 v[210:213], v153 offset:54272
	ds_read_b128 v[214:217], v153 offset:55296
	global_load_lds_dwordx4 v132, s[98:99]
	s_mov_b32 m0, s45
	ds_read_b128 v[218:221], v153 offset:56320
	global_load_lds_dwordx4 v138, s[30:31]
	s_mov_b32 m0, s46
	s_nop 0
	global_load_lds_dwordx4 v134, s[30:31]
	s_waitcnt vmcnt(8)
	s_waitcnt lgkmcnt(0)
	s_barrier
	v_mfma_f32_16x16x32_bf16 v[64:67], v[144:147], v[190:193], v[64:67]
	v_mfma_f32_16x16x32_bf16 v[64:67], v[154:157], v[194:197], v[64:67]
	v_mfma_f32_16x16x32_bf16 v[60:63], v[158:161], v[190:193], v[60:63]
	v_mfma_f32_16x16x32_bf16 v[60:63], v[162:165], v[194:197], v[60:63]
	v_mfma_f32_16x16x32_bf16 v[48:51], v[144:147], v[198:201], v[48:51]
	v_mfma_f32_16x16x32_bf16 v[48:51], v[154:157], v[202:205], v[48:51]
	v_mfma_f32_16x16x32_bf16 v[44:47], v[158:161], v[198:201], v[44:47]
	v_mfma_f32_16x16x32_bf16 v[44:47], v[162:165], v[202:205], v[44:47]
	v_mfma_f32_16x16x32_bf16 v[32:35], v[144:147], v[206:209], v[32:35]
	v_mfma_f32_16x16x32_bf16 v[32:35], v[154:157], v[210:213], v[32:35]
	v_mfma_f32_16x16x32_bf16 v[28:31], v[158:161], v[206:209], v[28:31]
	v_mfma_f32_16x16x32_bf16 v[28:31], v[162:165], v[210:213], v[28:31]
	v_mfma_f32_16x16x32_bf16 v[16:19], v[144:147], v[214:217], v[16:19]
	v_mfma_f32_16x16x32_bf16 v[16:19], v[154:157], v[218:221], v[16:19]
	v_mfma_f32_16x16x32_bf16 v[12:15], v[158:161], v[214:217], v[12:15]
	v_mfma_f32_16x16x32_bf16 v[12:15], v[162:165], v[218:221], v[12:15]
	v_mfma_f32_16x16x32_bf16 v[56:59], v[166:169], v[190:193], v[56:59]
	v_mfma_f32_16x16x32_bf16 v[56:59], v[170:173], v[194:197], v[56:59]
	v_mfma_f32_16x16x32_bf16 v[52:55], v[174:177], v[190:193], v[52:55]
	v_mfma_f32_16x16x32_bf16 v[52:55], v[186:189], v[194:197], v[52:55]
	v_mfma_f32_16x16x32_bf16 v[40:43], v[166:169], v[198:201], v[40:43]
	v_mfma_f32_16x16x32_bf16 v[40:43], v[170:173], v[202:205], v[40:43]
	v_mfma_f32_16x16x32_bf16 v[36:39], v[174:177], v[198:201], v[36:39]
	v_mfma_f32_16x16x32_bf16 v[36:39], v[186:189], v[202:205], v[36:39]
	v_mfma_f32_16x16x32_bf16 v[24:27], v[166:169], v[206:209], v[24:27]
	v_mfma_f32_16x16x32_bf16 v[24:27], v[170:173], v[210:213], v[24:27]
	v_mfma_f32_16x16x32_bf16 v[20:23], v[174:177], v[206:209], v[20:23]
	v_mfma_f32_16x16x32_bf16 v[20:23], v[186:189], v[210:213], v[20:23]
	v_mfma_f32_16x16x32_bf16 v[8:11], v[166:169], v[214:217], v[8:11]
	v_mfma_f32_16x16x32_bf16 v[8:11], v[170:173], v[218:221], v[8:11]
	v_mfma_f32_16x16x32_bf16 v[4:7], v[174:177], v[214:217], v[4:7]
	v_mfma_f32_16x16x32_bf16 v[4:7], v[186:189], v[218:221], v[4:7]
	s_barrier
	s_add_i32 s20, s20, 2
	s_add_u32 s10, s10, 0x100
	s_addc_u32 s11, s11, 0
	s_add_u32 s0, s0, 0x100
	s_addc_u32 s1, s1, 0
	s_cmp_gt_u32 s20, 61
	s_cbranch_scc0 .LBB0_1226
	s_and_b64 vcc, exec, s[48:49]
	s_cbranch_vccz .LBB0_1229
	s_barrier
